# attention loop: 3 LDS buffers + mid-iteration barrier, exact max only on first tile then post-hoc power-of-two rescale; P8 conv epilogue: redundant DPP pads removed
# speedup vs baseline: 1.0188x; 1.0108x over previous
.LBB0_214:
	v_ashrrev_i32_e32 v232, 4, v118
	v_lshlrev_b32_e32 v250, 7, v232
	v_ashrrev_i32_e32 v251, 31, v250
	v_and_b32_e32 v233, 0x78, v89
	v_lshl_add_u64 v[250:251], v[250:251], 1, s[74:75]
	v_lshlrev_b32_e32 v0, 1, v233
	v_lshl_add_u64 v[250:251], v[250:251], 0, v[0:1]
	s_mov_b64 s[86:87], 0x2000
	global_load_dwordx4 v[228:231], v[250:251], off
	v_lshl_add_u64 v[250:251], v[250:251], 0, s[86:87]
	global_load_dwordx4 v[242:245], v[250:251], off
	v_lshl_add_u64 v[250:251], v[250:251], 0, s[86:87]
	global_load_dwordx4 v[246:249], v[250:251], off
	v_lshl_add_u64 v[250:251], v[250:251], 0, s[86:87]
	global_load_dwordx4 v[164:167], v[250:251], off
	v_mad_u32_u24 v252, v232, s33, v233
	v_lshlrev_b32_e32 v252, 1, v252
	s_waitcnt vmcnt(0)
	ds_write_b128 v252, v[228:231]
	ds_write_b128 v252, v[242:245] offset:8704
	ds_write_b128 v252, v[246:249] offset:17408
	ds_write_b128 v252, v[164:167] offset:26112

.LBB0_219:
	v_ashrrev_i32_e32 v232, 4, v118
	v_lshlrev_b32_e32 v250, 7, v232
	v_ashrrev_i32_e32 v251, 31, v250
	v_and_b32_e32 v233, 0x78, v89
	v_lshl_add_u64 v[250:251], v[250:251], 1, s[76:77]
	v_lshlrev_b32_e32 v0, 1, v233
	v_lshl_add_u64 v[250:251], v[250:251], 0, v[0:1]
	s_mov_b64 s[54:55], 0x2000
	global_load_dwordx4 v[228:231], v[250:251], off
	v_lshl_add_u64 v[250:251], v[250:251], 0, s[54:55]
	global_load_dwordx4 v[242:245], v[250:251], off
	v_lshl_add_u64 v[250:251], v[250:251], 0, s[54:55]
	global_load_dwordx4 v[246:249], v[250:251], off
	v_lshl_add_u64 v[250:251], v[250:251], 0, s[54:55]
	global_load_dwordx4 v[164:167], v[250:251], off
	v_mad_u32_u24 v252, v232, s33, v233
	v_lshlrev_b32_e32 v252, 1, v252
	s_waitcnt vmcnt(0)
	ds_write_b128 v252, v[228:231]
	ds_write_b128 v252, v[242:245] offset:8704
	ds_write_b128 v252, v[246:249] offset:17408
	ds_write_b128 v252, v[164:167] offset:26112

.LBB0_226:
	v_ashrrev_i32_e32 v232, 4, v118
	v_lshlrev_b32_e32 v250, 7, v232
	v_ashrrev_i32_e32 v251, 31, v250
	v_and_b32_e32 v233, 0x78, v89
	v_lshl_add_u64 v[250:251], v[250:251], 1, s[80:81]
	v_lshlrev_b32_e32 v0, 1, v233
	v_lshl_add_u64 v[250:251], v[250:251], 0, v[0:1]
	s_mov_b64 s[42:43], 0x2000
	global_load_dwordx4 v[228:231], v[250:251], off
	v_lshl_add_u64 v[250:251], v[250:251], 0, s[42:43]
	global_load_dwordx4 v[242:245], v[250:251], off
	v_lshl_add_u64 v[250:251], v[250:251], 0, s[42:43]
	global_load_dwordx4 v[246:249], v[250:251], off
	v_lshl_add_u64 v[250:251], v[250:251], 0, s[42:43]
	global_load_dwordx4 v[164:167], v[250:251], off
	v_mad_u32_u24 v252, v232, s33, v233
	v_lshlrev_b32_e32 v252, 1, v252
	s_waitcnt vmcnt(0)
	ds_write_b128 v252, v[228:231]
	ds_write_b128 v252, v[242:245] offset:8704
	ds_write_b128 v252, v[246:249] offset:17408
	ds_write_b128 v252, v[164:167] offset:26112

.LBB0_231:
	v_ashrrev_i32_e32 v232, 4, v118
	v_lshlrev_b32_e32 v250, 7, v232
	v_ashrrev_i32_e32 v251, 31, v250
	v_and_b32_e32 v233, 0x78, v89
	v_lshl_add_u64 v[250:251], v[250:251], 1, s[78:79]
	v_lshlrev_b32_e32 v0, 1, v233
	v_lshl_add_u64 v[250:251], v[250:251], 0, v[0:1]
	s_mov_b64 s[46:47], 0x2000
	global_load_dwordx4 v[228:231], v[250:251], off
	v_lshl_add_u64 v[250:251], v[250:251], 0, s[46:47]
	global_load_dwordx4 v[242:245], v[250:251], off
	v_lshl_add_u64 v[250:251], v[250:251], 0, s[46:47]
	global_load_dwordx4 v[246:249], v[250:251], off
	v_lshl_add_u64 v[250:251], v[250:251], 0, s[46:47]
	global_load_dwordx4 v[164:167], v[250:251], off
	v_mad_u32_u24 v252, v232, s33, v233
	v_lshlrev_b32_e32 v252, 1, v252
	s_waitcnt vmcnt(0)
	ds_write_b128 v252, v[228:231]
	ds_write_b128 v252, v[242:245] offset:8704
	ds_write_b128 v252, v[246:249] offset:17408
	ds_write_b128 v252, v[164:167] offset:26112
	s_branch .LBB0_208

.LBB0_521:
	s_xor_b32 s10, s16, s14
	s_lshl_b32 s8, s10, 8
	s_lshl_b32 s7, s16, 9
	s_and_b32 s11, s8, 0x100
	s_or_b32 s62, s11, s7
	v_lshl_add_u64 v[134:135], v[122:123], 0, s[62:63]
	v_mad_u64_u32 v[2:3], s[8:9], v134, s59, v[124:125]
	v_mov_b32_e32 v0, v3
	v_mad_u64_u32 v[4:5], s[8:9], v135, s59, v[0:1]
	v_mov_b32_e32 v3, v4
	global_load_dwordx4 v[66:69], v[2:3], off
	global_load_dwordx4 v[70:73], v[2:3], off offset:32
	global_load_dwordx4 v[74:77], v[2:3], off offset:64
	global_load_dwordx4 v[78:81], v[2:3], off offset:96
	global_load_dwordx4 v[82:85], v[2:3], off offset:128
	global_load_dwordx4 v[86:89], v[2:3], off offset:160
	s_waitcnt lgkmcnt(0)
	s_barrier
	global_load_dwordx4 v[90:93], v[126:127], off
	global_load_dwordx4 v[94:97], v[126:127], off offset:128
	v_mov_b32_e32 v2, v1
	v_mov_b32_e32 v3, v1
	v_mov_b32_e32 v0, v1
	s_waitcnt vmcnt(16)
	v_mov_b64_e32 v[100:101], v[2:3]
	v_mov_b64_e32 v[98:99], v[0:1]
	global_load_dwordx4 v[98:101], v[128:129], off
	global_load_dwordx4 v[220:223], v[132:133], off
	global_load_dwordx4 v[224:227], v[132:133], off offset:128
	global_load_dwordx4 v[228:231], v[130:131], off
	s_mov_b64 s[24:25], 0x20000
	v_lshl_add_u64 v[136:137], v[132:133], 0, s[24:25]
	v_lshl_add_u64 v[138:139], v[130:131], 0, s[30:31]
	global_load_dwordx4 v[242:245], v[136:137], off
	global_load_dwordx4 v[246:249], v[136:137], off offset:128
	global_load_dwordx4 v[164:167], v[138:139], off
	v_lshl_add_u64 v[136:137], v[136:137], 0, s[24:25]
	v_lshl_add_u64 v[138:139], v[138:139], 0, s[30:31]
	v_add_u32_e32 v0, 0, v112
	s_waitcnt vmcnt(3)
	ds_write_b128 v0, v[90:93]
	v_add_u32_e32 v0, 0, v113
	s_nop 0
	ds_write_b128 v0, v[94:97] offset:13312
	s_and_saveexec_b64 s[8:9], s[0:1]
	v_add_u32_e32 v0, 0, v115
	ds_write_b128 v0, v[98:101] offset:128
	s_or_b64 exec, exec, s[8:9]
	ds_write_b128 v112, v[220:223] offset:22528
	ds_write_b128 v113, v[224:227] offset:35840
	ds_write_b128 v115, v[228:231] offset:22656
	global_load_dwordx4 v[90:93], v[136:137], off
	global_load_dwordx4 v[94:97], v[136:137], off offset:128
	global_load_dwordx4 v[98:101], v[138:139], off
	v_lshl_add_u64 v[136:137], v[136:137], 0, s[24:25]
	v_lshl_add_u64 v[138:139], v[138:139], 0, s[30:31]
	s_add_i32 s8, s15, s11
	s_lshr_b32 s8, s8, 6
	v_mov_b32_e32 v14, v1
	v_mov_b32_e32 v15, v1
	s_waitcnt lgkmcnt(0)
	s_barrier
	s_sub_i32 s18, 0, s8
	s_and_b32 s8, s10, 1
	v_mov_b32_e32 v0, v1
	v_mov_b32_e32 v2, v1
	v_mov_b32_e32 v3, v1
	v_mov_b32_e32 v4, v1
	v_mov_b32_e32 v5, v1
	v_mov_b32_e32 v6, v1
	v_mov_b32_e32 v7, v1
	v_mov_b32_e32 v8, v1
	v_mov_b32_e32 v9, v1
	v_mov_b32_e32 v10, v1
	v_mov_b32_e32 v11, v1
	v_mov_b32_e32 v12, v1
	v_mov_b32_e32 v13, v1
	v_mov_b64_e32 v[32:33], v[14:15]
	s_add_i32 s7, s62, 0x100
	s_lshl_b32 s8, s8, 8
	v_mov_b64_e32 v[30:31], v[12:13]
	v_mov_b64_e32 v[28:29], v[10:11]
	v_mov_b64_e32 v[26:27], v[8:9]
	v_mov_b64_e32 v[24:25], v[6:7]
	v_mov_b64_e32 v[22:23], v[4:5]
	v_mov_b64_e32 v[20:21], v[2:3]
	v_mov_b64_e32 v[18:19], v[0:1]
	v_mov_b64_e32 v[16:17], v[14:15]
	s_lshr_b32 s7, s7, 6
	s_mov_b32 s19, 1
	s_sub_i32 s20, 0, s8
	v_subrev_u32_e32 v121, s11, v114
	v_mov_b32_e32 v144, 0xf149f2ca
	v_mov_b32_e32 v143, 0
	s_nop 0
	s_nop 0
	s_mov_b32 s21, s17
	v_mov_b64_e32 v[14:15], v[12:13]
	v_mov_b64_e32 v[12:13], v[10:11]
	v_mov_b64_e32 v[10:11], v[8:9]
	v_mov_b64_e32 v[8:9], v[6:7]
	v_mov_b64_e32 v[6:7], v[4:5]
	v_mov_b64_e32 v[4:5], v[2:3]
	v_mov_b64_e32 v[2:3], v[0:1]
	v_mov_b32_e32 v146, 0
	v_mov_b32_e32 v147, 0
	v_mov_b32_e32 v148, 0
	v_mov_b32_e32 v149, 0
	v_mov_b32_e32 v150, 0
	v_mov_b32_e32 v151, 0
	v_mov_b32_e32 v152, 0
	v_mov_b32_e32 v153, 0
	v_mov_b32_e32 v154, 0
	v_mov_b32_e32 v155, 0
	v_mov_b32_e32 v156, 0
	v_mov_b32_e32 v157, 0
	v_mov_b32_e32 v158, 0
	v_mov_b32_e32 v159, 0
	v_mov_b32_e32 v160, 0
	v_mov_b32_e32 v161, 0
	v_mov_b32_e32 v169, v142
	v_add_u32_e32 v250, 22528, v142
	v_add_u32_e32 v251, 45056, v142
	s_add_i32 s22, s19, -1
	s_add_i32 s12, s22, s18
	s_cmp_gt_i32 s12, -5
	s_cselect_b64 s[10:11], -1, 0
	s_mov_b32 s26, 1
	s_cmp_lt_i32 s12, -4
	s_cbranch_scc1 .Lat_ctl_init
	v_readfirstlane_b32 s13, v109
	s_lshl_b32 s13, s13, 5
	s_add_i32 s12, s20, s21
	s_or_b32 s13, s13, 31
	s_cmp_le_i32 s12, s13
	s_cselect_b32 s26, 1, 0
.Lat_ctl_init:
	s_branch .Lat_head0
.Lat_head0:
	s_cmp_eq_u32 s26, 0
	s_cbranch_scc1 .Lat_skip0
	s_cmp_lg_u32 s22, 0
	s_cbranch_scc1 .Lat_fast0
	ds_read_b128 v[170:173], v140
	ds_read_b128 v[174:177], v140 offset:32
	ds_read_b128 v[178:181], v140 offset:64
	ds_read_b128 v[182:185], v140 offset:96
	ds_read_b128 v[186:189], v140 offset:128
	ds_read_b128 v[190:193], v140 offset:160
	ds_read_b128 v[204:207], v141
	ds_read_b128 v[208:211], v141 offset:32
	s_add_i32 s23, s19, 3
	s_cmp_ge_u32 s23, s7
	s_cbranch_scc1 .Lat_noissue_x0
	global_load_dwordx4 v[220:223], v[136:137], off
	global_load_dwordx4 v[224:227], v[136:137], off offset:128
	global_load_dwordx4 v[228:231], v[138:139], off
.Lat_noissue_x0:
	s_waitcnt lgkmcnt(7)
	v_mfma_f32_32x32x16_bf16 v[50:65], v[170:173], v[66:69], v[146:161]
	ds_read_b128 v[170:173], v141 offset:64
	s_waitcnt lgkmcnt(7)
	v_mfma_f32_32x32x16_bf16 v[50:65], v[174:177], v[70:73], v[50:65]
	ds_read_b128 v[174:177], v141 offset:96
	s_waitcnt lgkmcnt(7)
	v_mfma_f32_32x32x16_bf16 v[50:65], v[178:181], v[74:77], v[50:65]
	ds_read_b128 v[178:181], v141 offset:128
	s_waitcnt lgkmcnt(7)
	v_mfma_f32_32x32x16_bf16 v[50:65], v[182:185], v[78:81], v[50:65]
	ds_read_b128 v[182:185], v141 offset:160
	s_waitcnt lgkmcnt(7)
	v_mfma_f32_32x32x16_bf16 v[50:65], v[186:189], v[82:85], v[50:65]
	s_waitcnt lgkmcnt(6)
	v_mfma_f32_32x32x16_bf16 v[50:65], v[190:193], v[86:89], v[50:65]
	ds_read_b64_tr_b16 v[186:187], v169 offset:13312
	ds_read_b64_tr_b16 v[188:189], v169 offset:14464
	ds_read_b64_tr_b16 v[190:191], v169 offset:13376
	ds_read_b64_tr_b16 v[192:193], v169 offset:14528
	s_nop 7
	s_nop 1
	s_andn2_b64 vcc, exec, s[10:11]
	s_cbranch_vccnz .Lat_xnomaskA0
	v_add_u32_e32 v0, s21, v121
	v_mov_b32_e32 v145, v0
	v_add_u32_e32 v168, 1, v0
	v_cmp_le_i32_e64 vcc, v145, v102
	v_add_u32_e32 v252, 2, v0
	v_cmp_le_i32_e64 s[28:29], v168, v102
	v_cndmask_b32_e64 v50, v203, v50, vcc
	v_add_u32_e32 v145, 3, v0
	v_cmp_le_i32_e64 vcc, v252, v102
	v_cndmask_b32_e64 v51, v203, v51, s[28:29]
	v_add_u32_e32 v168, 8, v0
	v_cmp_le_i32_e64 s[28:29], v145, v102
	v_cndmask_b32_e64 v52, v203, v52, vcc
	v_add_u32_e32 v252, 9, v0
	v_cmp_le_i32_e64 vcc, v168, v102
	v_cndmask_b32_e64 v53, v203, v53, s[28:29]
	v_add_u32_e32 v145, 10, v0
	v_cmp_le_i32_e64 s[28:29], v252, v102
	v_cndmask_b32_e64 v54, v203, v54, vcc
	v_add_u32_e32 v168, 11, v0
	v_cmp_le_i32_e64 vcc, v145, v102
	v_cndmask_b32_e64 v55, v203, v55, s[28:29]
	v_add_u32_e32 v252, 16, v0
	v_cmp_le_i32_e64 s[28:29], v168, v102
	v_cndmask_b32_e64 v56, v203, v56, vcc
	v_add_u32_e32 v145, 17, v0
	v_cmp_le_i32_e64 vcc, v252, v102
	v_cndmask_b32_e64 v57, v203, v57, s[28:29]
	v_add_u32_e32 v168, 18, v0
	v_cmp_le_i32_e64 s[28:29], v145, v102
	v_cndmask_b32_e64 v58, v203, v58, vcc
	v_add_u32_e32 v252, 19, v0
	v_cmp_le_i32_e64 vcc, v168, v102
	v_cndmask_b32_e64 v59, v203, v59, s[28:29]
	v_add_u32_e32 v145, 24, v0
	v_cmp_le_i32_e64 s[28:29], v252, v102
	v_cndmask_b32_e64 v60, v203, v60, vcc
	v_add_u32_e32 v168, 25, v0
	v_cmp_le_i32_e64 vcc, v145, v102
	v_cndmask_b32_e64 v61, v203, v61, s[28:29]
	v_add_u32_e32 v252, 26, v0
	v_cmp_le_i32_e64 s[28:29], v168, v102
	v_cndmask_b32_e64 v62, v203, v62, vcc
	v_add_u32_e32 v145, 27, v0
	v_cmp_le_i32_e64 vcc, v252, v102
	v_cndmask_b32_e64 v63, v203, v63, s[28:29]
	v_cmp_le_i32_e64 s[28:29], v145, v102
	v_cndmask_b32_e64 v64, v203, v64, vcc
	s_nop 1
	v_cndmask_b32_e64 v65, v203, v65, s[28:29]
.Lat_xnomaskA0:
	v_max3_f32 v232, v50, v51, v52
	v_max3_f32 v233, v53, v54, v55
	v_max3_f32 v232, v232, v56, v57
	v_max3_f32 v233, v233, v58, v59
	v_max3_f32 v232, v232, v60, v61
	v_max3_f32 v233, v233, v62, v63
	v_max3_f32 v232, v232, v64, v65
	v_max_f32_e32 v232, v232, v233
	v_mov_b32_e32 v233, v232
	s_nop 1
	v_permlane32_swap_b32_e32 v232, v233
	v_max_f32_e32 v232, v232, v233
	v_sub_f32_e32 v50, v50, v232
	v_sub_f32_e32 v51, v51, v232
	v_sub_f32_e32 v52, v52, v232
	v_sub_f32_e32 v53, v53, v232
	v_sub_f32_e32 v54, v54, v232
	v_sub_f32_e32 v55, v55, v232
	v_sub_f32_e32 v56, v56, v232
	v_sub_f32_e32 v57, v57, v232
	v_sub_f32_e32 v58, v58, v232
	v_sub_f32_e32 v59, v59, v232
	v_sub_f32_e32 v60, v60, v232
	v_sub_f32_e32 v61, v61, v232
	v_sub_f32_e32 v62, v62, v232
	v_sub_f32_e32 v63, v63, v232
	v_sub_f32_e32 v64, v64, v232
	v_sub_f32_e32 v65, v65, v232
	v_sub_f32_e32 v146, v146, v232
	s_nop 0
	v_mov_b32_e32 v147, v146
	v_mov_b32_e32 v148, v146
	v_mov_b32_e32 v149, v146
	v_mov_b32_e32 v150, v146
	v_mov_b32_e32 v151, v146
	v_mov_b32_e32 v152, v146
	v_mov_b32_e32 v153, v146
	v_mov_b32_e32 v154, v146
	v_mov_b32_e32 v155, v146
	v_mov_b32_e32 v156, v146
	v_mov_b32_e32 v157, v146
	v_mov_b32_e32 v158, v146
	v_mov_b32_e32 v159, v146
	v_mov_b32_e32 v160, v146
	v_mov_b32_e32 v161, v146
	s_nop 1
	s_waitcnt lgkmcnt(9)
	v_mfma_f32_32x32x16_bf16 v[34:49], v[204:207], v[66:69], v[146:161]
	ds_read_b64_tr_b16 v[204:205], v169 offset:15616
	ds_read_b64_tr_b16 v[206:207], v169 offset:16768
	s_waitcnt lgkmcnt(10)
	v_mfma_f32_32x32x16_bf16 v[34:49], v[208:211], v[70:73], v[34:49]
	ds_read_b64_tr_b16 v[208:209], v169 offset:15680
	ds_read_b64_tr_b16 v[210:211], v169 offset:16832
	v_exp_f32_e32 v50, v50
	v_exp_f32_e32 v51, v51
	v_exp_f32_e32 v52, v52
	v_exp_f32_e32 v53, v53
	s_waitcnt lgkmcnt(11)
	v_mfma_f32_32x32x16_bf16 v[34:49], v[170:173], v[74:77], v[34:49]
	v_exp_f32_e32 v54, v54
	v_exp_f32_e32 v55, v55
	v_exp_f32_e32 v56, v56
	v_exp_f32_e32 v57, v57
	v_cvt_pk_bf16_f32 v212, v50, v51
	v_cvt_pk_bf16_f32 v213, v52, v53
	v_cvt_pk_bf16_f32 v214, v54, v55
	v_cvt_pk_bf16_f32 v215, v56, v57
	s_waitcnt lgkmcnt(10)
	v_mfma_f32_32x32x16_bf16 v[34:49], v[174:177], v[78:81], v[34:49]
	v_add_f32_e32 v163, v50, v52
	v_add_f32_e32 v237, v51, v53
	s_waitcnt lgkmcnt(6)
	v_mfma_f32_32x32x16_bf16 v[18:33], v[186:189], v[212:215], v[18:33]
	v_exp_f32_e32 v58, v58
	v_exp_f32_e32 v59, v59
	v_exp_f32_e32 v60, v60
	s_waitcnt lgkmcnt(4)
	v_mfma_f32_32x32x16_bf16 v[2:17], v[190:193], v[212:215], v[2:17]
	v_exp_f32_e32 v61, v61
	v_exp_f32_e32 v62, v62
	v_exp_f32_e32 v63, v63
	v_mfma_f32_32x32x16_bf16 v[34:49], v[178:181], v[82:85], v[34:49]
	v_exp_f32_e32 v64, v64
	v_exp_f32_e32 v65, v65
	v_add_f32_e32 v163, v163, v54
	v_add_f32_e32 v237, v237, v55
	v_mfma_f32_32x32x16_bf16 v[34:49], v[182:185], v[86:89], v[34:49]
	v_cvt_pk_bf16_f32 v216, v58, v59
	v_cvt_pk_bf16_f32 v217, v60, v61
	v_cvt_pk_bf16_f32 v218, v62, v63
	v_cvt_pk_bf16_f32 v219, v64, v65
	v_add_f32_e32 v163, v163, v56
	v_add_f32_e32 v237, v237, v57
	v_add_f32_e32 v163, v163, v58
	v_add_f32_e32 v237, v237, v59
	s_waitcnt lgkmcnt(2)
	v_mfma_f32_32x32x16_bf16 v[18:33], v[204:207], v[216:219], v[18:33]
	v_add_f32_e32 v163, v163, v60
	v_add_f32_e32 v237, v237, v61
	v_add_f32_e32 v163, v163, v62
	s_waitcnt lgkmcnt(0)
	v_mfma_f32_32x32x16_bf16 v[2:17], v[208:211], v[216:219], v[2:17]
	v_add_f32_e32 v237, v237, v63
	v_add_f32_e32 v163, v163, v64
	v_add_f32_e32 v237, v237, v65
	s_barrier
	ds_read_b64_tr_b16 v[170:171], v169 offset:17920
	ds_read_b64_tr_b16 v[172:173], v169 offset:19072
	ds_read_b64_tr_b16 v[174:175], v169 offset:17984
	ds_read_b64_tr_b16 v[176:177], v169 offset:19136
	ds_read_b64_tr_b16 v[178:179], v169 offset:20224
	ds_read_b64_tr_b16 v[180:181], v169 offset:21376
	ds_read_b64_tr_b16 v[182:183], v169 offset:20288
	ds_read_b64_tr_b16 v[184:185], v169 offset:21440
	s_add_i32 s23, s19, 3
	s_cmp_lt_u32 s23, s7
	s_cbranch_scc1 .Lat_w6_x0
	s_add_i32 s23, s19, 2
	s_cmp_lt_u32 s23, s7
	s_cbranch_scc1 .Lat_w3_x0
	s_waitcnt vmcnt(0)
	s_branch .Lat_wd_x0
.Lat_w3_x0:
	s_waitcnt vmcnt(3)
	s_branch .Lat_wd_x0
.Lat_w6_x0:
	s_waitcnt vmcnt(6)
.Lat_wd_x0:
	ds_write_b128 v112, v[242:245] offset:45056
	ds_write_b128 v113, v[246:249] offset:58368
	ds_write_b128 v115, v[164:167] offset:45184
	s_andn2_b64 vcc, exec, s[10:11]
	s_cbranch_vccnz .Lat_xnomaskB0
	v_add_u32_e32 v0, s21, v121
	v_add_u32_e32 v145, 32, v0
	v_add_u32_e32 v168, 33, v0
	v_cmp_le_i32_e64 vcc, v145, v102
	v_add_u32_e32 v252, 34, v0
	v_cmp_le_i32_e64 s[28:29], v168, v102
	v_cndmask_b32_e64 v34, v203, v34, vcc
	v_add_u32_e32 v145, 35, v0
	v_cmp_le_i32_e64 vcc, v252, v102
	v_cndmask_b32_e64 v35, v203, v35, s[28:29]
	v_add_u32_e32 v168, 40, v0
	v_cmp_le_i32_e64 s[28:29], v145, v102
	v_cndmask_b32_e64 v36, v203, v36, vcc
	v_add_u32_e32 v252, 41, v0
	v_cmp_le_i32_e64 vcc, v168, v102
	v_cndmask_b32_e64 v37, v203, v37, s[28:29]
	v_add_u32_e32 v145, 42, v0
	v_cmp_le_i32_e64 s[28:29], v252, v102
	v_cndmask_b32_e64 v38, v203, v38, vcc
	v_add_u32_e32 v168, 43, v0
	v_cmp_le_i32_e64 vcc, v145, v102
	v_cndmask_b32_e64 v39, v203, v39, s[28:29]
	v_add_u32_e32 v252, 48, v0
	v_cmp_le_i32_e64 s[28:29], v168, v102
	v_cndmask_b32_e64 v40, v203, v40, vcc
	v_add_u32_e32 v145, 49, v0
	v_cmp_le_i32_e64 vcc, v252, v102
	v_cndmask_b32_e64 v41, v203, v41, s[28:29]
	v_add_u32_e32 v168, 50, v0
	v_cmp_le_i32_e64 s[28:29], v145, v102
	v_cndmask_b32_e64 v42, v203, v42, vcc
	v_add_u32_e32 v252, 51, v0
	v_cmp_le_i32_e64 vcc, v168, v102
	v_cndmask_b32_e64 v43, v203, v43, s[28:29]
	v_add_u32_e32 v145, 56, v0
	v_cmp_le_i32_e64 s[28:29], v252, v102
	v_cndmask_b32_e64 v44, v203, v44, vcc
	v_add_u32_e32 v168, 57, v0
	v_cmp_le_i32_e64 vcc, v145, v102
	v_cndmask_b32_e64 v45, v203, v45, s[28:29]
	v_add_u32_e32 v252, 58, v0
	v_cmp_le_i32_e64 s[28:29], v168, v102
	v_cndmask_b32_e64 v46, v203, v46, vcc
	v_add_u32_e32 v145, 59, v0
	v_cmp_le_i32_e64 vcc, v252, v102
	v_cndmask_b32_e64 v47, v203, v47, s[28:29]
	v_cmp_le_i32_e64 s[28:29], v145, v102
	v_cndmask_b32_e64 v48, v203, v48, vcc
	s_nop 1
	v_cndmask_b32_e64 v49, v203, v49, s[28:29]

.Lat_commonB0:
	v_exp_f32_e32 v34, v34
	v_exp_f32_e32 v35, v35
	v_exp_f32_e32 v36, v36
	v_exp_f32_e32 v37, v37
	v_exp_f32_e32 v38, v38
	v_exp_f32_e32 v39, v39
	v_exp_f32_e32 v40, v40
	v_exp_f32_e32 v41, v41
	v_cvt_pk_bf16_f32 v212, v34, v35
	v_cvt_pk_bf16_f32 v213, v36, v37
	v_cvt_pk_bf16_f32 v214, v38, v39
	v_cvt_pk_bf16_f32 v215, v40, v41
	v_exp_f32_e32 v42, v42
	v_exp_f32_e32 v43, v43
	s_waitcnt lgkmcnt(9)
	v_mfma_f32_32x32x16_bf16 v[18:33], v[170:173], v[212:215], v[18:33]
	s_waitcnt lgkmcnt(7)
	v_mfma_f32_32x32x16_bf16 v[2:17], v[174:177], v[212:215], v[2:17]
	v_exp_f32_e32 v44, v44
	v_add_f32_e32 v163, v163, v34
	v_exp_f32_e32 v45, v45
	v_add_f32_e32 v237, v237, v35
	v_exp_f32_e32 v46, v46
	v_add_f32_e32 v163, v163, v36
	v_exp_f32_e32 v47, v47
	v_add_f32_e32 v237, v237, v37
	v_exp_f32_e32 v48, v48
	v_add_f32_e32 v163, v163, v38
	v_exp_f32_e32 v49, v49
	v_add_f32_e32 v237, v237, v39
	v_add_f32_e32 v163, v163, v40
	v_add_f32_e32 v237, v237, v41
	v_cvt_pk_bf16_f32 v216, v42, v43
	v_cvt_pk_bf16_f32 v217, v44, v45
	v_cvt_pk_bf16_f32 v218, v46, v47
	v_cvt_pk_bf16_f32 v219, v48, v49
	v_add_f32_e32 v163, v163, v42
	v_add_f32_e32 v237, v237, v43
	s_waitcnt lgkmcnt(5)
	v_mfma_f32_32x32x16_bf16 v[18:33], v[178:181], v[216:219], v[18:33]
	s_waitcnt lgkmcnt(3)
	v_mfma_f32_32x32x16_bf16 v[2:17], v[182:185], v[216:219], v[2:17]
	v_add_f32_e32 v163, v163, v44
	v_add_f32_e32 v237, v237, v45
	v_add_f32_e32 v163, v163, v46
	v_add_f32_e32 v237, v237, v47
	v_add_f32_e32 v163, v163, v48
	v_add_f32_e32 v237, v237, v49
	v_add_f32_e32 v163, v163, v237
	v_cmp_lt_f32_e32 vcc, 0x45800000, v163
	v_add_f32_e32 v143, v143, v163
	s_cbranch_vccnz .Lat_postx0

.Lat_fast0:
	ds_read_b128 v[170:173], v140
	ds_read_b128 v[174:177], v140 offset:32
	ds_read_b128 v[178:181], v140 offset:64
	ds_read_b128 v[182:185], v140 offset:96
	ds_read_b128 v[186:189], v140 offset:128
	ds_read_b128 v[190:193], v140 offset:160
	ds_read_b128 v[204:207], v141
	ds_read_b128 v[208:211], v141 offset:32
	s_add_i32 s23, s19, 3
	s_cmp_ge_u32 s23, s7
	s_cbranch_scc1 .Lat_noissue_f0
	global_load_dwordx4 v[220:223], v[136:137], off
	global_load_dwordx4 v[224:227], v[136:137], off offset:128
	global_load_dwordx4 v[228:231], v[138:139], off
.Lat_noissue_f0:
	s_waitcnt lgkmcnt(7)
	v_mfma_f32_32x32x16_bf16 v[50:65], v[170:173], v[66:69], v[146:161]
	ds_read_b128 v[170:173], v141 offset:64
	s_waitcnt lgkmcnt(7)
	v_mfma_f32_32x32x16_bf16 v[50:65], v[174:177], v[70:73], v[50:65]
	ds_read_b128 v[174:177], v141 offset:96
	s_waitcnt lgkmcnt(7)
	v_mfma_f32_32x32x16_bf16 v[50:65], v[178:181], v[74:77], v[50:65]
	ds_read_b128 v[178:181], v141 offset:128
	s_waitcnt lgkmcnt(7)
	v_mfma_f32_32x32x16_bf16 v[50:65], v[182:185], v[78:81], v[50:65]
	ds_read_b128 v[182:185], v141 offset:160
	s_waitcnt lgkmcnt(7)
	v_mfma_f32_32x32x16_bf16 v[50:65], v[186:189], v[82:85], v[50:65]
	s_waitcnt lgkmcnt(6)
	v_mfma_f32_32x32x16_bf16 v[50:65], v[190:193], v[86:89], v[50:65]
	ds_read_b64_tr_b16 v[186:187], v169 offset:13312
	ds_read_b64_tr_b16 v[188:189], v169 offset:14464
	ds_read_b64_tr_b16 v[190:191], v169 offset:13376
	ds_read_b64_tr_b16 v[192:193], v169 offset:14528
	s_waitcnt lgkmcnt(9)
	v_mfma_f32_32x32x16_bf16 v[34:49], v[204:207], v[66:69], v[146:161]
	ds_read_b64_tr_b16 v[204:205], v169 offset:15616
	ds_read_b64_tr_b16 v[206:207], v169 offset:16768
	s_waitcnt lgkmcnt(10)
	v_mfma_f32_32x32x16_bf16 v[34:49], v[208:211], v[70:73], v[34:49]
	ds_read_b64_tr_b16 v[208:209], v169 offset:15680
	ds_read_b64_tr_b16 v[210:211], v169 offset:16832
	s_nop 3
	s_andn2_b64 vcc, exec, s[10:11]
	s_cbranch_vccnz .Lat_fnomaskA0
	v_add_u32_e32 v0, s21, v121
	v_mov_b32_e32 v145, v0
	v_add_u32_e32 v168, 1, v0
	v_cmp_le_i32_e64 vcc, v145, v102
	v_add_u32_e32 v252, 2, v0
	v_cmp_le_i32_e64 s[28:29], v168, v102
	v_cndmask_b32_e64 v50, v203, v50, vcc
	v_add_u32_e32 v145, 3, v0
	v_cmp_le_i32_e64 vcc, v252, v102
	v_cndmask_b32_e64 v51, v203, v51, s[28:29]
	v_add_u32_e32 v168, 8, v0
	v_cmp_le_i32_e64 s[28:29], v145, v102
	v_cndmask_b32_e64 v52, v203, v52, vcc
	v_add_u32_e32 v252, 9, v0
	v_cmp_le_i32_e64 vcc, v168, v102
	v_cndmask_b32_e64 v53, v203, v53, s[28:29]
	v_add_u32_e32 v145, 10, v0
	v_cmp_le_i32_e64 s[28:29], v252, v102
	v_cndmask_b32_e64 v54, v203, v54, vcc
	v_add_u32_e32 v168, 11, v0
	v_cmp_le_i32_e64 vcc, v145, v102
	v_cndmask_b32_e64 v55, v203, v55, s[28:29]
	v_add_u32_e32 v252, 16, v0
	v_cmp_le_i32_e64 s[28:29], v168, v102
	v_cndmask_b32_e64 v56, v203, v56, vcc
	v_add_u32_e32 v145, 17, v0
	v_cmp_le_i32_e64 vcc, v252, v102
	v_cndmask_b32_e64 v57, v203, v57, s[28:29]
	v_add_u32_e32 v168, 18, v0
	v_cmp_le_i32_e64 s[28:29], v145, v102
	v_cndmask_b32_e64 v58, v203, v58, vcc
	v_add_u32_e32 v252, 19, v0
	v_cmp_le_i32_e64 vcc, v168, v102
	v_cndmask_b32_e64 v59, v203, v59, s[28:29]
	v_add_u32_e32 v145, 24, v0
	v_cmp_le_i32_e64 s[28:29], v252, v102
	v_cndmask_b32_e64 v60, v203, v60, vcc
	v_add_u32_e32 v168, 25, v0
	v_cmp_le_i32_e64 vcc, v145, v102
	v_cndmask_b32_e64 v61, v203, v61, s[28:29]
	v_add_u32_e32 v252, 26, v0
	v_cmp_le_i32_e64 s[28:29], v168, v102
	v_cndmask_b32_e64 v62, v203, v62, vcc
	v_add_u32_e32 v145, 27, v0
	v_cmp_le_i32_e64 vcc, v252, v102
	v_cndmask_b32_e64 v63, v203, v63, s[28:29]
	v_cmp_le_i32_e64 s[28:29], v145, v102
	v_cndmask_b32_e64 v64, v203, v64, vcc
	s_nop 1
	v_cndmask_b32_e64 v65, v203, v65, s[28:29]
.Lat_fnomaskA0:
	v_exp_f32_e32 v50, v50
	v_exp_f32_e32 v51, v51
	v_exp_f32_e32 v52, v52
	v_exp_f32_e32 v53, v53
	s_waitcnt lgkmcnt(11)
	v_mfma_f32_32x32x16_bf16 v[34:49], v[170:173], v[74:77], v[34:49]
	v_exp_f32_e32 v54, v54
	v_exp_f32_e32 v55, v55
	v_exp_f32_e32 v56, v56
	v_exp_f32_e32 v57, v57
	v_cvt_pk_bf16_f32 v212, v50, v51
	v_cvt_pk_bf16_f32 v213, v52, v53
	v_cvt_pk_bf16_f32 v214, v54, v55
	v_cvt_pk_bf16_f32 v215, v56, v57
	s_waitcnt lgkmcnt(10)
	v_mfma_f32_32x32x16_bf16 v[34:49], v[174:177], v[78:81], v[34:49]
	v_add_f32_e32 v163, v50, v52
	v_add_f32_e32 v237, v51, v53
	s_waitcnt lgkmcnt(6)
	v_mfma_f32_32x32x16_bf16 v[18:33], v[186:189], v[212:215], v[18:33]
	v_exp_f32_e32 v58, v58
	v_exp_f32_e32 v59, v59
	v_exp_f32_e32 v60, v60
	s_waitcnt lgkmcnt(4)
	v_mfma_f32_32x32x16_bf16 v[2:17], v[190:193], v[212:215], v[2:17]
	v_exp_f32_e32 v61, v61
	v_exp_f32_e32 v62, v62
	v_exp_f32_e32 v63, v63
	v_mfma_f32_32x32x16_bf16 v[34:49], v[178:181], v[82:85], v[34:49]
	v_exp_f32_e32 v64, v64
	v_exp_f32_e32 v65, v65
	v_add_f32_e32 v163, v163, v54
	v_add_f32_e32 v237, v237, v55
	v_mfma_f32_32x32x16_bf16 v[34:49], v[182:185], v[86:89], v[34:49]
	v_cvt_pk_bf16_f32 v216, v58, v59
	v_cvt_pk_bf16_f32 v217, v60, v61
	v_cvt_pk_bf16_f32 v218, v62, v63
	v_cvt_pk_bf16_f32 v219, v64, v65
	v_add_f32_e32 v163, v163, v56
	v_add_f32_e32 v237, v237, v57
	v_add_f32_e32 v163, v163, v58
	v_add_f32_e32 v237, v237, v59
	s_waitcnt lgkmcnt(2)
	v_mfma_f32_32x32x16_bf16 v[18:33], v[204:207], v[216:219], v[18:33]
	v_add_f32_e32 v163, v163, v60
	v_add_f32_e32 v237, v237, v61
	v_add_f32_e32 v163, v163, v62
	s_waitcnt lgkmcnt(0)
	v_mfma_f32_32x32x16_bf16 v[2:17], v[208:211], v[216:219], v[2:17]
	v_add_f32_e32 v237, v237, v63
	v_add_f32_e32 v163, v163, v64
	v_add_f32_e32 v237, v237, v65
	s_barrier
	ds_read_b64_tr_b16 v[170:171], v169 offset:17920
	ds_read_b64_tr_b16 v[172:173], v169 offset:19072
	ds_read_b64_tr_b16 v[174:175], v169 offset:17984
	ds_read_b64_tr_b16 v[176:177], v169 offset:19136
	ds_read_b64_tr_b16 v[178:179], v169 offset:20224
	ds_read_b64_tr_b16 v[180:181], v169 offset:21376
	ds_read_b64_tr_b16 v[182:183], v169 offset:20288
	ds_read_b64_tr_b16 v[184:185], v169 offset:21440
	s_add_i32 s23, s19, 3
	s_cmp_lt_u32 s23, s7
	s_cbranch_scc1 .Lat_w6_f0
	s_add_i32 s23, s19, 2
	s_cmp_lt_u32 s23, s7
	s_cbranch_scc1 .Lat_w3_f0
	s_waitcnt vmcnt(0)
	s_branch .Lat_wd_f0

.Lat_skip0:
	s_add_i32 s23, s19, 3
	s_cmp_ge_u32 s23, s7
	s_cbranch_scc1 .Lat_noissue_s0
	global_load_dwordx4 v[220:223], v[136:137], off
	global_load_dwordx4 v[224:227], v[136:137], off offset:128
	global_load_dwordx4 v[228:231], v[138:139], off
.Lat_noissue_s0:
	s_waitcnt lgkmcnt(0)
	s_barrier
	s_add_i32 s23, s19, 3
	s_cmp_lt_u32 s23, s7
	s_cbranch_scc1 .Lat_w6_s0
	s_add_i32 s23, s19, 2
	s_cmp_lt_u32 s23, s7
	s_cbranch_scc1 .Lat_w3_s0
	s_waitcnt vmcnt(0)
	s_branch .Lat_wd_s0

.Lat_wd_s0:
	ds_write_b128 v112, v[242:245] offset:45056
	ds_write_b128 v113, v[246:249] offset:58368
	ds_write_b128 v115, v[164:167] offset:45184
.Lat_tail0:
	s_add_i32 s19, s19, 1
	s_add_i32 s21, s21, 64
	s_mov_b64 s[28:29], 0x20000
	v_lshl_add_u64 v[138:139], v[138:139], 0, s[30:31]
	v_lshl_add_u64 v[136:137], v[136:137], 0, s[28:29]
	s_add_i32 s8, s18, s19
	s_cmp_lg_u32 s8, 1
	s_cselect_b32 s25, 0, 1
	s_add_i32 s22, s19, -1
	s_add_i32 s12, s22, s18
	s_cmp_gt_i32 s12, -5
	s_cselect_b64 s[10:11], -1, 0
	s_mov_b32 s26, 1
	s_cmp_lt_i32 s12, -4
	s_cbranch_scc1 .Lat_ctl_t0
	v_readfirstlane_b32 s13, v109
	s_lshl_b32 s13, s13, 5
	s_add_i32 s12, s20, s21
	s_or_b32 s13, s13, 31
	s_cmp_le_i32 s12, s13
	s_cselect_b32 s26, 1, 0
.Lat_ctl_t0:
	s_cmp_eq_u32 s25, 1
	s_cbranch_scc1 .LBB0_520
.Lat_head1:
	s_cmp_eq_u32 s26, 0
	s_cbranch_scc1 .Lat_skip1
	s_cmp_lg_u32 s22, 0
	s_cbranch_scc1 .Lat_fast1
	ds_read_b128 v[170:173], v140 offset:22528
	ds_read_b128 v[174:177], v140 offset:22560
	ds_read_b128 v[178:181], v140 offset:22592
	ds_read_b128 v[182:185], v140 offset:22624
	ds_read_b128 v[186:189], v140 offset:22656
	ds_read_b128 v[190:193], v140 offset:22688
	ds_read_b128 v[204:207], v141 offset:22528
	ds_read_b128 v[208:211], v141 offset:22560
	s_add_i32 s23, s19, 3
	s_cmp_ge_u32 s23, s7
	s_cbranch_scc1 .Lat_noissue_x1
	global_load_dwordx4 v[242:245], v[136:137], off
	global_load_dwordx4 v[246:249], v[136:137], off offset:128
	global_load_dwordx4 v[164:167], v[138:139], off
.Lat_noissue_x1:
	s_waitcnt lgkmcnt(7)
	v_mfma_f32_32x32x16_bf16 v[50:65], v[170:173], v[66:69], v[146:161]
	ds_read_b128 v[170:173], v141 offset:22592
	s_waitcnt lgkmcnt(7)
	v_mfma_f32_32x32x16_bf16 v[50:65], v[174:177], v[70:73], v[50:65]
	ds_read_b128 v[174:177], v141 offset:22624
	s_waitcnt lgkmcnt(7)
	v_mfma_f32_32x32x16_bf16 v[50:65], v[178:181], v[74:77], v[50:65]
	ds_read_b128 v[178:181], v141 offset:22656
	s_waitcnt lgkmcnt(7)
	v_mfma_f32_32x32x16_bf16 v[50:65], v[182:185], v[78:81], v[50:65]
	ds_read_b128 v[182:185], v141 offset:22688
	s_waitcnt lgkmcnt(7)
	v_mfma_f32_32x32x16_bf16 v[50:65], v[186:189], v[82:85], v[50:65]
	s_waitcnt lgkmcnt(6)
	v_mfma_f32_32x32x16_bf16 v[50:65], v[190:193], v[86:89], v[50:65]
	ds_read_b64_tr_b16 v[186:187], v250 offset:13312
	ds_read_b64_tr_b16 v[188:189], v250 offset:14464
	ds_read_b64_tr_b16 v[190:191], v250 offset:13376
	ds_read_b64_tr_b16 v[192:193], v250 offset:14528
	s_nop 7
	s_nop 1
	s_andn2_b64 vcc, exec, s[10:11]
	s_cbranch_vccnz .Lat_xnomaskA1
	v_add_u32_e32 v0, s21, v121
	v_mov_b32_e32 v145, v0
	v_add_u32_e32 v168, 1, v0
	v_cmp_le_i32_e64 vcc, v145, v102
	v_add_u32_e32 v252, 2, v0
	v_cmp_le_i32_e64 s[28:29], v168, v102
	v_cndmask_b32_e64 v50, v203, v50, vcc
	v_add_u32_e32 v145, 3, v0
	v_cmp_le_i32_e64 vcc, v252, v102
	v_cndmask_b32_e64 v51, v203, v51, s[28:29]
	v_add_u32_e32 v168, 8, v0
	v_cmp_le_i32_e64 s[28:29], v145, v102
	v_cndmask_b32_e64 v52, v203, v52, vcc
	v_add_u32_e32 v252, 9, v0
	v_cmp_le_i32_e64 vcc, v168, v102
	v_cndmask_b32_e64 v53, v203, v53, s[28:29]
	v_add_u32_e32 v145, 10, v0
	v_cmp_le_i32_e64 s[28:29], v252, v102
	v_cndmask_b32_e64 v54, v203, v54, vcc
	v_add_u32_e32 v168, 11, v0
	v_cmp_le_i32_e64 vcc, v145, v102
	v_cndmask_b32_e64 v55, v203, v55, s[28:29]
	v_add_u32_e32 v252, 16, v0
	v_cmp_le_i32_e64 s[28:29], v168, v102
	v_cndmask_b32_e64 v56, v203, v56, vcc
	v_add_u32_e32 v145, 17, v0
	v_cmp_le_i32_e64 vcc, v252, v102
	v_cndmask_b32_e64 v57, v203, v57, s[28:29]
	v_add_u32_e32 v168, 18, v0
	v_cmp_le_i32_e64 s[28:29], v145, v102
	v_cndmask_b32_e64 v58, v203, v58, vcc
	v_add_u32_e32 v252, 19, v0
	v_cmp_le_i32_e64 vcc, v168, v102
	v_cndmask_b32_e64 v59, v203, v59, s[28:29]
	v_add_u32_e32 v145, 24, v0
	v_cmp_le_i32_e64 s[28:29], v252, v102
	v_cndmask_b32_e64 v60, v203, v60, vcc
	v_add_u32_e32 v168, 25, v0
	v_cmp_le_i32_e64 vcc, v145, v102
	v_cndmask_b32_e64 v61, v203, v61, s[28:29]
	v_add_u32_e32 v252, 26, v0
	v_cmp_le_i32_e64 s[28:29], v168, v102
	v_cndmask_b32_e64 v62, v203, v62, vcc
	v_add_u32_e32 v145, 27, v0
	v_cmp_le_i32_e64 vcc, v252, v102
	v_cndmask_b32_e64 v63, v203, v63, s[28:29]
	v_cmp_le_i32_e64 s[28:29], v145, v102
	v_cndmask_b32_e64 v64, v203, v64, vcc
	s_nop 1
	v_cndmask_b32_e64 v65, v203, v65, s[28:29]
.Lat_xnomaskA1:
	v_max3_f32 v232, v50, v51, v52
	v_max3_f32 v233, v53, v54, v55
	v_max3_f32 v232, v232, v56, v57
	v_max3_f32 v233, v233, v58, v59
	v_max3_f32 v232, v232, v60, v61
	v_max3_f32 v233, v233, v62, v63
	v_max3_f32 v232, v232, v64, v65
	v_max_f32_e32 v232, v232, v233
	v_mov_b32_e32 v233, v232
	s_nop 1
	v_permlane32_swap_b32_e32 v232, v233
	v_max_f32_e32 v232, v232, v233
	v_sub_f32_e32 v50, v50, v232
	v_sub_f32_e32 v51, v51, v232
	v_sub_f32_e32 v52, v52, v232
	v_sub_f32_e32 v53, v53, v232
	v_sub_f32_e32 v54, v54, v232
	v_sub_f32_e32 v55, v55, v232
	v_sub_f32_e32 v56, v56, v232
	v_sub_f32_e32 v57, v57, v232
	v_sub_f32_e32 v58, v58, v232
	v_sub_f32_e32 v59, v59, v232
	v_sub_f32_e32 v60, v60, v232
	v_sub_f32_e32 v61, v61, v232
	v_sub_f32_e32 v62, v62, v232
	v_sub_f32_e32 v63, v63, v232
	v_sub_f32_e32 v64, v64, v232
	v_sub_f32_e32 v65, v65, v232
	v_sub_f32_e32 v146, v146, v232
	s_nop 0
	v_mov_b32_e32 v147, v146
	v_mov_b32_e32 v148, v146
	v_mov_b32_e32 v149, v146
	v_mov_b32_e32 v150, v146
	v_mov_b32_e32 v151, v146
	v_mov_b32_e32 v152, v146
	v_mov_b32_e32 v153, v146
	v_mov_b32_e32 v154, v146
	v_mov_b32_e32 v155, v146
	v_mov_b32_e32 v156, v146
	v_mov_b32_e32 v157, v146
	v_mov_b32_e32 v158, v146
	v_mov_b32_e32 v159, v146
	v_mov_b32_e32 v160, v146
	v_mov_b32_e32 v161, v146
	s_nop 1
	s_waitcnt lgkmcnt(9)
	v_mfma_f32_32x32x16_bf16 v[34:49], v[204:207], v[66:69], v[146:161]
	ds_read_b64_tr_b16 v[204:205], v250 offset:15616
	ds_read_b64_tr_b16 v[206:207], v250 offset:16768
	s_waitcnt lgkmcnt(10)
	v_mfma_f32_32x32x16_bf16 v[34:49], v[208:211], v[70:73], v[34:49]
	ds_read_b64_tr_b16 v[208:209], v250 offset:15680
	ds_read_b64_tr_b16 v[210:211], v250 offset:16832
	v_exp_f32_e32 v50, v50
	v_exp_f32_e32 v51, v51
	v_exp_f32_e32 v52, v52
	v_exp_f32_e32 v53, v53
	s_waitcnt lgkmcnt(11)
	v_mfma_f32_32x32x16_bf16 v[34:49], v[170:173], v[74:77], v[34:49]
	v_exp_f32_e32 v54, v54
	v_exp_f32_e32 v55, v55
	v_exp_f32_e32 v56, v56
	v_exp_f32_e32 v57, v57
	v_cvt_pk_bf16_f32 v212, v50, v51
	v_cvt_pk_bf16_f32 v213, v52, v53
	v_cvt_pk_bf16_f32 v214, v54, v55
	v_cvt_pk_bf16_f32 v215, v56, v57
	s_waitcnt lgkmcnt(10)
	v_mfma_f32_32x32x16_bf16 v[34:49], v[174:177], v[78:81], v[34:49]
	v_add_f32_e32 v163, v50, v52
	v_add_f32_e32 v237, v51, v53
	s_waitcnt lgkmcnt(6)
	v_mfma_f32_32x32x16_bf16 v[18:33], v[186:189], v[212:215], v[18:33]
	v_exp_f32_e32 v58, v58
	v_exp_f32_e32 v59, v59
	v_exp_f32_e32 v60, v60
	s_waitcnt lgkmcnt(4)
	v_mfma_f32_32x32x16_bf16 v[2:17], v[190:193], v[212:215], v[2:17]
	v_exp_f32_e32 v61, v61
	v_exp_f32_e32 v62, v62
	v_exp_f32_e32 v63, v63
	v_mfma_f32_32x32x16_bf16 v[34:49], v[178:181], v[82:85], v[34:49]
	v_exp_f32_e32 v64, v64
	v_exp_f32_e32 v65, v65
	v_add_f32_e32 v163, v163, v54
	v_add_f32_e32 v237, v237, v55
	v_mfma_f32_32x32x16_bf16 v[34:49], v[182:185], v[86:89], v[34:49]
	v_cvt_pk_bf16_f32 v216, v58, v59
	v_cvt_pk_bf16_f32 v217, v60, v61
	v_cvt_pk_bf16_f32 v218, v62, v63
	v_cvt_pk_bf16_f32 v219, v64, v65
	v_add_f32_e32 v163, v163, v56
	v_add_f32_e32 v237, v237, v57
	v_add_f32_e32 v163, v163, v58
	v_add_f32_e32 v237, v237, v59
	s_waitcnt lgkmcnt(2)
	v_mfma_f32_32x32x16_bf16 v[18:33], v[204:207], v[216:219], v[18:33]
	v_add_f32_e32 v163, v163, v60
	v_add_f32_e32 v237, v237, v61
	v_add_f32_e32 v163, v163, v62
	s_waitcnt lgkmcnt(0)
	v_mfma_f32_32x32x16_bf16 v[2:17], v[208:211], v[216:219], v[2:17]
	v_add_f32_e32 v237, v237, v63
	v_add_f32_e32 v163, v163, v64
	v_add_f32_e32 v237, v237, v65
	s_barrier
	ds_read_b64_tr_b16 v[170:171], v250 offset:17920
	ds_read_b64_tr_b16 v[172:173], v250 offset:19072
	ds_read_b64_tr_b16 v[174:175], v250 offset:17984
	ds_read_b64_tr_b16 v[176:177], v250 offset:19136
	ds_read_b64_tr_b16 v[178:179], v250 offset:20224
	ds_read_b64_tr_b16 v[180:181], v250 offset:21376
	ds_read_b64_tr_b16 v[182:183], v250 offset:20288
	ds_read_b64_tr_b16 v[184:185], v250 offset:21440
	s_add_i32 s23, s19, 3
	s_cmp_lt_u32 s23, s7
	s_cbranch_scc1 .Lat_w6_x1
	s_add_i32 s23, s19, 2
	s_cmp_lt_u32 s23, s7
	s_cbranch_scc1 .Lat_w3_x1
	s_waitcnt vmcnt(0)
	s_branch .Lat_wd_x1

.Lat_wd_x1:
	ds_write_b128 v112, v[90:93]
	ds_write_b128 v113, v[94:97] offset:13312
	ds_write_b128 v115, v[98:101] offset:128
	s_andn2_b64 vcc, exec, s[10:11]
	s_cbranch_vccnz .Lat_xnomaskB1
	v_add_u32_e32 v0, s21, v121
	v_add_u32_e32 v145, 32, v0
	v_add_u32_e32 v168, 33, v0
	v_cmp_le_i32_e64 vcc, v145, v102
	v_add_u32_e32 v252, 34, v0
	v_cmp_le_i32_e64 s[28:29], v168, v102
	v_cndmask_b32_e64 v34, v203, v34, vcc
	v_add_u32_e32 v145, 35, v0
	v_cmp_le_i32_e64 vcc, v252, v102
	v_cndmask_b32_e64 v35, v203, v35, s[28:29]
	v_add_u32_e32 v168, 40, v0
	v_cmp_le_i32_e64 s[28:29], v145, v102
	v_cndmask_b32_e64 v36, v203, v36, vcc
	v_add_u32_e32 v252, 41, v0
	v_cmp_le_i32_e64 vcc, v168, v102
	v_cndmask_b32_e64 v37, v203, v37, s[28:29]
	v_add_u32_e32 v145, 42, v0
	v_cmp_le_i32_e64 s[28:29], v252, v102
	v_cndmask_b32_e64 v38, v203, v38, vcc
	v_add_u32_e32 v168, 43, v0
	v_cmp_le_i32_e64 vcc, v145, v102
	v_cndmask_b32_e64 v39, v203, v39, s[28:29]
	v_add_u32_e32 v252, 48, v0
	v_cmp_le_i32_e64 s[28:29], v168, v102
	v_cndmask_b32_e64 v40, v203, v40, vcc
	v_add_u32_e32 v145, 49, v0
	v_cmp_le_i32_e64 vcc, v252, v102
	v_cndmask_b32_e64 v41, v203, v41, s[28:29]
	v_add_u32_e32 v168, 50, v0
	v_cmp_le_i32_e64 s[28:29], v145, v102
	v_cndmask_b32_e64 v42, v203, v42, vcc
	v_add_u32_e32 v252, 51, v0
	v_cmp_le_i32_e64 vcc, v168, v102
	v_cndmask_b32_e64 v43, v203, v43, s[28:29]
	v_add_u32_e32 v145, 56, v0
	v_cmp_le_i32_e64 s[28:29], v252, v102
	v_cndmask_b32_e64 v44, v203, v44, vcc
	v_add_u32_e32 v168, 57, v0
	v_cmp_le_i32_e64 vcc, v145, v102
	v_cndmask_b32_e64 v45, v203, v45, s[28:29]
	v_add_u32_e32 v252, 58, v0
	v_cmp_le_i32_e64 s[28:29], v168, v102
	v_cndmask_b32_e64 v46, v203, v46, vcc
	v_add_u32_e32 v145, 59, v0
	v_cmp_le_i32_e64 vcc, v252, v102
	v_cndmask_b32_e64 v47, v203, v47, s[28:29]
	v_cmp_le_i32_e64 s[28:29], v145, v102
	v_cndmask_b32_e64 v48, v203, v48, vcc
	s_nop 1
	v_cndmask_b32_e64 v49, v203, v49, s[28:29]

.Lat_fast1:
	ds_read_b128 v[170:173], v140 offset:22528
	ds_read_b128 v[174:177], v140 offset:22560
	ds_read_b128 v[178:181], v140 offset:22592
	ds_read_b128 v[182:185], v140 offset:22624
	ds_read_b128 v[186:189], v140 offset:22656
	ds_read_b128 v[190:193], v140 offset:22688
	ds_read_b128 v[204:207], v141 offset:22528
	ds_read_b128 v[208:211], v141 offset:22560
	s_add_i32 s23, s19, 3
	s_cmp_ge_u32 s23, s7
	s_cbranch_scc1 .Lat_noissue_f1
	global_load_dwordx4 v[242:245], v[136:137], off
	global_load_dwordx4 v[246:249], v[136:137], off offset:128
	global_load_dwordx4 v[164:167], v[138:139], off
.Lat_noissue_f1:
	s_waitcnt lgkmcnt(7)
	v_mfma_f32_32x32x16_bf16 v[50:65], v[170:173], v[66:69], v[146:161]
	ds_read_b128 v[170:173], v141 offset:22592
	s_waitcnt lgkmcnt(7)
	v_mfma_f32_32x32x16_bf16 v[50:65], v[174:177], v[70:73], v[50:65]
	ds_read_b128 v[174:177], v141 offset:22624
	s_waitcnt lgkmcnt(7)
	v_mfma_f32_32x32x16_bf16 v[50:65], v[178:181], v[74:77], v[50:65]
	ds_read_b128 v[178:181], v141 offset:22656
	s_waitcnt lgkmcnt(7)
	v_mfma_f32_32x32x16_bf16 v[50:65], v[182:185], v[78:81], v[50:65]
	ds_read_b128 v[182:185], v141 offset:22688
	s_waitcnt lgkmcnt(7)
	v_mfma_f32_32x32x16_bf16 v[50:65], v[186:189], v[82:85], v[50:65]
	s_waitcnt lgkmcnt(6)
	v_mfma_f32_32x32x16_bf16 v[50:65], v[190:193], v[86:89], v[50:65]
	ds_read_b64_tr_b16 v[186:187], v250 offset:13312
	ds_read_b64_tr_b16 v[188:189], v250 offset:14464
	ds_read_b64_tr_b16 v[190:191], v250 offset:13376
	ds_read_b64_tr_b16 v[192:193], v250 offset:14528
	s_waitcnt lgkmcnt(9)
	v_mfma_f32_32x32x16_bf16 v[34:49], v[204:207], v[66:69], v[146:161]
	ds_read_b64_tr_b16 v[204:205], v250 offset:15616
	ds_read_b64_tr_b16 v[206:207], v250 offset:16768
	s_waitcnt lgkmcnt(10)
	v_mfma_f32_32x32x16_bf16 v[34:49], v[208:211], v[70:73], v[34:49]
	ds_read_b64_tr_b16 v[208:209], v250 offset:15680
	ds_read_b64_tr_b16 v[210:211], v250 offset:16832
	s_nop 3
	s_andn2_b64 vcc, exec, s[10:11]
	s_cbranch_vccnz .Lat_fnomaskA1
	v_add_u32_e32 v0, s21, v121
	v_mov_b32_e32 v145, v0
	v_add_u32_e32 v168, 1, v0
	v_cmp_le_i32_e64 vcc, v145, v102
	v_add_u32_e32 v252, 2, v0
	v_cmp_le_i32_e64 s[28:29], v168, v102
	v_cndmask_b32_e64 v50, v203, v50, vcc
	v_add_u32_e32 v145, 3, v0
	v_cmp_le_i32_e64 vcc, v252, v102
	v_cndmask_b32_e64 v51, v203, v51, s[28:29]
	v_add_u32_e32 v168, 8, v0
	v_cmp_le_i32_e64 s[28:29], v145, v102
	v_cndmask_b32_e64 v52, v203, v52, vcc
	v_add_u32_e32 v252, 9, v0
	v_cmp_le_i32_e64 vcc, v168, v102
	v_cndmask_b32_e64 v53, v203, v53, s[28:29]
	v_add_u32_e32 v145, 10, v0
	v_cmp_le_i32_e64 s[28:29], v252, v102
	v_cndmask_b32_e64 v54, v203, v54, vcc
	v_add_u32_e32 v168, 11, v0
	v_cmp_le_i32_e64 vcc, v145, v102
	v_cndmask_b32_e64 v55, v203, v55, s[28:29]
	v_add_u32_e32 v252, 16, v0
	v_cmp_le_i32_e64 s[28:29], v168, v102
	v_cndmask_b32_e64 v56, v203, v56, vcc
	v_add_u32_e32 v145, 17, v0
	v_cmp_le_i32_e64 vcc, v252, v102
	v_cndmask_b32_e64 v57, v203, v57, s[28:29]
	v_add_u32_e32 v168, 18, v0
	v_cmp_le_i32_e64 s[28:29], v145, v102
	v_cndmask_b32_e64 v58, v203, v58, vcc
	v_add_u32_e32 v252, 19, v0
	v_cmp_le_i32_e64 vcc, v168, v102
	v_cndmask_b32_e64 v59, v203, v59, s[28:29]
	v_add_u32_e32 v145, 24, v0
	v_cmp_le_i32_e64 s[28:29], v252, v102
	v_cndmask_b32_e64 v60, v203, v60, vcc
	v_add_u32_e32 v168, 25, v0
	v_cmp_le_i32_e64 vcc, v145, v102
	v_cndmask_b32_e64 v61, v203, v61, s[28:29]
	v_add_u32_e32 v252, 26, v0
	v_cmp_le_i32_e64 s[28:29], v168, v102
	v_cndmask_b32_e64 v62, v203, v62, vcc
	v_add_u32_e32 v145, 27, v0
	v_cmp_le_i32_e64 vcc, v252, v102
	v_cndmask_b32_e64 v63, v203, v63, s[28:29]
	v_cmp_le_i32_e64 s[28:29], v145, v102
	v_cndmask_b32_e64 v64, v203, v64, vcc
	s_nop 1
	v_cndmask_b32_e64 v65, v203, v65, s[28:29]
.Lat_fnomaskA1:
	v_exp_f32_e32 v50, v50
	v_exp_f32_e32 v51, v51
	v_exp_f32_e32 v52, v52
	v_exp_f32_e32 v53, v53
	s_waitcnt lgkmcnt(11)
	v_mfma_f32_32x32x16_bf16 v[34:49], v[170:173], v[74:77], v[34:49]
	v_exp_f32_e32 v54, v54
	v_exp_f32_e32 v55, v55
	v_exp_f32_e32 v56, v56
	v_exp_f32_e32 v57, v57
	v_cvt_pk_bf16_f32 v212, v50, v51
	v_cvt_pk_bf16_f32 v213, v52, v53
	v_cvt_pk_bf16_f32 v214, v54, v55
	v_cvt_pk_bf16_f32 v215, v56, v57
	s_waitcnt lgkmcnt(10)
	v_mfma_f32_32x32x16_bf16 v[34:49], v[174:177], v[78:81], v[34:49]
	v_add_f32_e32 v163, v50, v52
	v_add_f32_e32 v237, v51, v53
	s_waitcnt lgkmcnt(6)
	v_mfma_f32_32x32x16_bf16 v[18:33], v[186:189], v[212:215], v[18:33]
	v_exp_f32_e32 v58, v58
	v_exp_f32_e32 v59, v59
	v_exp_f32_e32 v60, v60
	s_waitcnt lgkmcnt(4)
	v_mfma_f32_32x32x16_bf16 v[2:17], v[190:193], v[212:215], v[2:17]
	v_exp_f32_e32 v61, v61
	v_exp_f32_e32 v62, v62
	v_exp_f32_e32 v63, v63
	v_mfma_f32_32x32x16_bf16 v[34:49], v[178:181], v[82:85], v[34:49]
	v_exp_f32_e32 v64, v64
	v_exp_f32_e32 v65, v65
	v_add_f32_e32 v163, v163, v54
	v_add_f32_e32 v237, v237, v55
	v_mfma_f32_32x32x16_bf16 v[34:49], v[182:185], v[86:89], v[34:49]
	v_cvt_pk_bf16_f32 v216, v58, v59
	v_cvt_pk_bf16_f32 v217, v60, v61
	v_cvt_pk_bf16_f32 v218, v62, v63
	v_cvt_pk_bf16_f32 v219, v64, v65
	v_add_f32_e32 v163, v163, v56
	v_add_f32_e32 v237, v237, v57
	v_add_f32_e32 v163, v163, v58
	v_add_f32_e32 v237, v237, v59
	s_waitcnt lgkmcnt(2)
	v_mfma_f32_32x32x16_bf16 v[18:33], v[204:207], v[216:219], v[18:33]
	v_add_f32_e32 v163, v163, v60
	v_add_f32_e32 v237, v237, v61
	v_add_f32_e32 v163, v163, v62
	s_waitcnt lgkmcnt(0)
	v_mfma_f32_32x32x16_bf16 v[2:17], v[208:211], v[216:219], v[2:17]
	v_add_f32_e32 v237, v237, v63
	v_add_f32_e32 v163, v163, v64
	v_add_f32_e32 v237, v237, v65
	s_barrier
	ds_read_b64_tr_b16 v[170:171], v250 offset:17920
	ds_read_b64_tr_b16 v[172:173], v250 offset:19072
	ds_read_b64_tr_b16 v[174:175], v250 offset:17984
	ds_read_b64_tr_b16 v[176:177], v250 offset:19136
	ds_read_b64_tr_b16 v[178:179], v250 offset:20224
	ds_read_b64_tr_b16 v[180:181], v250 offset:21376
	ds_read_b64_tr_b16 v[182:183], v250 offset:20288
	ds_read_b64_tr_b16 v[184:185], v250 offset:21440
	s_add_i32 s23, s19, 3
	s_cmp_lt_u32 s23, s7
	s_cbranch_scc1 .Lat_w6_f1
	s_add_i32 s23, s19, 2
	s_cmp_lt_u32 s23, s7
	s_cbranch_scc1 .Lat_w3_f1
	s_waitcnt vmcnt(0)
	s_branch .Lat_wd_f1

.Lat_skip1:
	s_add_i32 s23, s19, 3
	s_cmp_ge_u32 s23, s7
	s_cbranch_scc1 .Lat_noissue_s1
	global_load_dwordx4 v[242:245], v[136:137], off
	global_load_dwordx4 v[246:249], v[136:137], off offset:128
	global_load_dwordx4 v[164:167], v[138:139], off

.Lat_wd_s1:
	ds_write_b128 v112, v[90:93]
	ds_write_b128 v113, v[94:97] offset:13312
	ds_write_b128 v115, v[98:101] offset:128

.Lat_head2:
	s_cmp_eq_u32 s26, 0
	s_cbranch_scc1 .Lat_skip2
	s_cmp_lg_u32 s22, 0
	s_cbranch_scc1 .Lat_fast2
	ds_read_b128 v[170:173], v140 offset:45056
	ds_read_b128 v[174:177], v140 offset:45088
	ds_read_b128 v[178:181], v140 offset:45120
	ds_read_b128 v[182:185], v140 offset:45152
	ds_read_b128 v[186:189], v140 offset:45184
	ds_read_b128 v[190:193], v140 offset:45216
	ds_read_b128 v[204:207], v141 offset:45056
	ds_read_b128 v[208:211], v141 offset:45088
	s_add_i32 s23, s19, 3
	s_cmp_ge_u32 s23, s7
	s_cbranch_scc1 .Lat_noissue_x2
	global_load_dwordx4 v[90:93], v[136:137], off
	global_load_dwordx4 v[94:97], v[136:137], off offset:128
	global_load_dwordx4 v[98:101], v[138:139], off
.Lat_noissue_x2:
	s_waitcnt lgkmcnt(7)
	v_mfma_f32_32x32x16_bf16 v[50:65], v[170:173], v[66:69], v[146:161]
	ds_read_b128 v[170:173], v141 offset:45120
	s_waitcnt lgkmcnt(7)
	v_mfma_f32_32x32x16_bf16 v[50:65], v[174:177], v[70:73], v[50:65]
	ds_read_b128 v[174:177], v141 offset:45152
	s_waitcnt lgkmcnt(7)
	v_mfma_f32_32x32x16_bf16 v[50:65], v[178:181], v[74:77], v[50:65]
	ds_read_b128 v[178:181], v141 offset:45184
	s_waitcnt lgkmcnt(7)
	v_mfma_f32_32x32x16_bf16 v[50:65], v[182:185], v[78:81], v[50:65]
	ds_read_b128 v[182:185], v141 offset:45216
	s_waitcnt lgkmcnt(7)
	v_mfma_f32_32x32x16_bf16 v[50:65], v[186:189], v[82:85], v[50:65]
	s_waitcnt lgkmcnt(6)
	v_mfma_f32_32x32x16_bf16 v[50:65], v[190:193], v[86:89], v[50:65]
	ds_read_b64_tr_b16 v[186:187], v251 offset:13312
	ds_read_b64_tr_b16 v[188:189], v251 offset:14464
	ds_read_b64_tr_b16 v[190:191], v251 offset:13376
	ds_read_b64_tr_b16 v[192:193], v251 offset:14528
	s_nop 7
	s_nop 1
	s_andn2_b64 vcc, exec, s[10:11]
	s_cbranch_vccnz .Lat_xnomaskA2
	v_add_u32_e32 v0, s21, v121
	v_mov_b32_e32 v145, v0
	v_add_u32_e32 v168, 1, v0
	v_cmp_le_i32_e64 vcc, v145, v102
	v_add_u32_e32 v252, 2, v0
	v_cmp_le_i32_e64 s[28:29], v168, v102
	v_cndmask_b32_e64 v50, v203, v50, vcc
	v_add_u32_e32 v145, 3, v0
	v_cmp_le_i32_e64 vcc, v252, v102
	v_cndmask_b32_e64 v51, v203, v51, s[28:29]
	v_add_u32_e32 v168, 8, v0
	v_cmp_le_i32_e64 s[28:29], v145, v102
	v_cndmask_b32_e64 v52, v203, v52, vcc
	v_add_u32_e32 v252, 9, v0
	v_cmp_le_i32_e64 vcc, v168, v102
	v_cndmask_b32_e64 v53, v203, v53, s[28:29]
	v_add_u32_e32 v145, 10, v0
	v_cmp_le_i32_e64 s[28:29], v252, v102
	v_cndmask_b32_e64 v54, v203, v54, vcc
	v_add_u32_e32 v168, 11, v0
	v_cmp_le_i32_e64 vcc, v145, v102
	v_cndmask_b32_e64 v55, v203, v55, s[28:29]
	v_add_u32_e32 v252, 16, v0
	v_cmp_le_i32_e64 s[28:29], v168, v102
	v_cndmask_b32_e64 v56, v203, v56, vcc
	v_add_u32_e32 v145, 17, v0
	v_cmp_le_i32_e64 vcc, v252, v102
	v_cndmask_b32_e64 v57, v203, v57, s[28:29]
	v_add_u32_e32 v168, 18, v0
	v_cmp_le_i32_e64 s[28:29], v145, v102
	v_cndmask_b32_e64 v58, v203, v58, vcc
	v_add_u32_e32 v252, 19, v0
	v_cmp_le_i32_e64 vcc, v168, v102
	v_cndmask_b32_e64 v59, v203, v59, s[28:29]
	v_add_u32_e32 v145, 24, v0
	v_cmp_le_i32_e64 s[28:29], v252, v102
	v_cndmask_b32_e64 v60, v203, v60, vcc
	v_add_u32_e32 v168, 25, v0
	v_cmp_le_i32_e64 vcc, v145, v102
	v_cndmask_b32_e64 v61, v203, v61, s[28:29]
	v_add_u32_e32 v252, 26, v0
	v_cmp_le_i32_e64 s[28:29], v168, v102
	v_cndmask_b32_e64 v62, v203, v62, vcc
	v_add_u32_e32 v145, 27, v0
	v_cmp_le_i32_e64 vcc, v252, v102
	v_cndmask_b32_e64 v63, v203, v63, s[28:29]
	v_cmp_le_i32_e64 s[28:29], v145, v102
	v_cndmask_b32_e64 v64, v203, v64, vcc
	s_nop 1
	v_cndmask_b32_e64 v65, v203, v65, s[28:29]
.Lat_xnomaskA2:
	v_max3_f32 v232, v50, v51, v52
	v_max3_f32 v233, v53, v54, v55
	v_max3_f32 v232, v232, v56, v57
	v_max3_f32 v233, v233, v58, v59
	v_max3_f32 v232, v232, v60, v61
	v_max3_f32 v233, v233, v62, v63
	v_max3_f32 v232, v232, v64, v65
	v_max_f32_e32 v232, v232, v233
	v_mov_b32_e32 v233, v232
	s_nop 1
	v_permlane32_swap_b32_e32 v232, v233
	v_max_f32_e32 v232, v232, v233
	v_sub_f32_e32 v50, v50, v232
	v_sub_f32_e32 v51, v51, v232
	v_sub_f32_e32 v52, v52, v232
	v_sub_f32_e32 v53, v53, v232
	v_sub_f32_e32 v54, v54, v232
	v_sub_f32_e32 v55, v55, v232
	v_sub_f32_e32 v56, v56, v232
	v_sub_f32_e32 v57, v57, v232
	v_sub_f32_e32 v58, v58, v232
	v_sub_f32_e32 v59, v59, v232
	v_sub_f32_e32 v60, v60, v232
	v_sub_f32_e32 v61, v61, v232
	v_sub_f32_e32 v62, v62, v232
	v_sub_f32_e32 v63, v63, v232
	v_sub_f32_e32 v64, v64, v232
	v_sub_f32_e32 v65, v65, v232
	v_sub_f32_e32 v146, v146, v232
	s_nop 0
	v_mov_b32_e32 v147, v146
	v_mov_b32_e32 v148, v146
	v_mov_b32_e32 v149, v146
	v_mov_b32_e32 v150, v146
	v_mov_b32_e32 v151, v146
	v_mov_b32_e32 v152, v146
	v_mov_b32_e32 v153, v146
	v_mov_b32_e32 v154, v146
	v_mov_b32_e32 v155, v146
	v_mov_b32_e32 v156, v146
	v_mov_b32_e32 v157, v146
	v_mov_b32_e32 v158, v146
	v_mov_b32_e32 v159, v146
	v_mov_b32_e32 v160, v146
	v_mov_b32_e32 v161, v146
	s_nop 1
	s_waitcnt lgkmcnt(9)
	v_mfma_f32_32x32x16_bf16 v[34:49], v[204:207], v[66:69], v[146:161]
	ds_read_b64_tr_b16 v[204:205], v251 offset:15616
	ds_read_b64_tr_b16 v[206:207], v251 offset:16768
	s_waitcnt lgkmcnt(10)
	v_mfma_f32_32x32x16_bf16 v[34:49], v[208:211], v[70:73], v[34:49]
	ds_read_b64_tr_b16 v[208:209], v251 offset:15680
	ds_read_b64_tr_b16 v[210:211], v251 offset:16832
	v_exp_f32_e32 v50, v50
	v_exp_f32_e32 v51, v51
	v_exp_f32_e32 v52, v52
	v_exp_f32_e32 v53, v53
	s_waitcnt lgkmcnt(11)
	v_mfma_f32_32x32x16_bf16 v[34:49], v[170:173], v[74:77], v[34:49]
	v_exp_f32_e32 v54, v54
	v_exp_f32_e32 v55, v55
	v_exp_f32_e32 v56, v56
	v_exp_f32_e32 v57, v57
	v_cvt_pk_bf16_f32 v212, v50, v51
	v_cvt_pk_bf16_f32 v213, v52, v53
	v_cvt_pk_bf16_f32 v214, v54, v55
	v_cvt_pk_bf16_f32 v215, v56, v57
	s_waitcnt lgkmcnt(10)
	v_mfma_f32_32x32x16_bf16 v[34:49], v[174:177], v[78:81], v[34:49]
	v_add_f32_e32 v163, v50, v52
	v_add_f32_e32 v237, v51, v53
	s_waitcnt lgkmcnt(6)
	v_mfma_f32_32x32x16_bf16 v[18:33], v[186:189], v[212:215], v[18:33]
	v_exp_f32_e32 v58, v58
	v_exp_f32_e32 v59, v59
	v_exp_f32_e32 v60, v60
	s_waitcnt lgkmcnt(4)
	v_mfma_f32_32x32x16_bf16 v[2:17], v[190:193], v[212:215], v[2:17]
	v_exp_f32_e32 v61, v61
	v_exp_f32_e32 v62, v62
	v_exp_f32_e32 v63, v63
	v_mfma_f32_32x32x16_bf16 v[34:49], v[178:181], v[82:85], v[34:49]
	v_exp_f32_e32 v64, v64
	v_exp_f32_e32 v65, v65
	v_add_f32_e32 v163, v163, v54
	v_add_f32_e32 v237, v237, v55
	v_mfma_f32_32x32x16_bf16 v[34:49], v[182:185], v[86:89], v[34:49]
	v_cvt_pk_bf16_f32 v216, v58, v59
	v_cvt_pk_bf16_f32 v217, v60, v61
	v_cvt_pk_bf16_f32 v218, v62, v63
	v_cvt_pk_bf16_f32 v219, v64, v65
	v_add_f32_e32 v163, v163, v56
	v_add_f32_e32 v237, v237, v57
	v_add_f32_e32 v163, v163, v58
	v_add_f32_e32 v237, v237, v59
	s_waitcnt lgkmcnt(2)
	v_mfma_f32_32x32x16_bf16 v[18:33], v[204:207], v[216:219], v[18:33]
	v_add_f32_e32 v163, v163, v60
	v_add_f32_e32 v237, v237, v61
	v_add_f32_e32 v163, v163, v62
	s_waitcnt lgkmcnt(0)
	v_mfma_f32_32x32x16_bf16 v[2:17], v[208:211], v[216:219], v[2:17]
	v_add_f32_e32 v237, v237, v63
	v_add_f32_e32 v163, v163, v64
	v_add_f32_e32 v237, v237, v65
	s_barrier
	ds_read_b64_tr_b16 v[170:171], v251 offset:17920
	ds_read_b64_tr_b16 v[172:173], v251 offset:19072
	ds_read_b64_tr_b16 v[174:175], v251 offset:17984
	ds_read_b64_tr_b16 v[176:177], v251 offset:19136
	ds_read_b64_tr_b16 v[178:179], v251 offset:20224
	ds_read_b64_tr_b16 v[180:181], v251 offset:21376
	ds_read_b64_tr_b16 v[182:183], v251 offset:20288
	ds_read_b64_tr_b16 v[184:185], v251 offset:21440
	s_add_i32 s23, s19, 3
	s_cmp_lt_u32 s23, s7
	s_cbranch_scc1 .Lat_w6_x2
	s_add_i32 s23, s19, 2
	s_cmp_lt_u32 s23, s7
	s_cbranch_scc1 .Lat_w3_x2
	s_waitcnt vmcnt(0)
	s_branch .Lat_wd_x2

.Lat_wd_x2:
	ds_write_b128 v112, v[220:223] offset:22528
	ds_write_b128 v113, v[224:227] offset:35840
	ds_write_b128 v115, v[228:231] offset:22656
	s_andn2_b64 vcc, exec, s[10:11]
	s_cbranch_vccnz .Lat_xnomaskB2
	v_add_u32_e32 v0, s21, v121
	v_add_u32_e32 v145, 32, v0
	v_add_u32_e32 v168, 33, v0
	v_cmp_le_i32_e64 vcc, v145, v102
	v_add_u32_e32 v252, 34, v0
	v_cmp_le_i32_e64 s[28:29], v168, v102
	v_cndmask_b32_e64 v34, v203, v34, vcc
	v_add_u32_e32 v145, 35, v0
	v_cmp_le_i32_e64 vcc, v252, v102
	v_cndmask_b32_e64 v35, v203, v35, s[28:29]
	v_add_u32_e32 v168, 40, v0
	v_cmp_le_i32_e64 s[28:29], v145, v102
	v_cndmask_b32_e64 v36, v203, v36, vcc
	v_add_u32_e32 v252, 41, v0
	v_cmp_le_i32_e64 vcc, v168, v102
	v_cndmask_b32_e64 v37, v203, v37, s[28:29]
	v_add_u32_e32 v145, 42, v0
	v_cmp_le_i32_e64 s[28:29], v252, v102
	v_cndmask_b32_e64 v38, v203, v38, vcc
	v_add_u32_e32 v168, 43, v0
	v_cmp_le_i32_e64 vcc, v145, v102
	v_cndmask_b32_e64 v39, v203, v39, s[28:29]
	v_add_u32_e32 v252, 48, v0
	v_cmp_le_i32_e64 s[28:29], v168, v102
	v_cndmask_b32_e64 v40, v203, v40, vcc
	v_add_u32_e32 v145, 49, v0
	v_cmp_le_i32_e64 vcc, v252, v102
	v_cndmask_b32_e64 v41, v203, v41, s[28:29]
	v_add_u32_e32 v168, 50, v0
	v_cmp_le_i32_e64 s[28:29], v145, v102
	v_cndmask_b32_e64 v42, v203, v42, vcc
	v_add_u32_e32 v252, 51, v0
	v_cmp_le_i32_e64 vcc, v168, v102
	v_cndmask_b32_e64 v43, v203, v43, s[28:29]
	v_add_u32_e32 v145, 56, v0
	v_cmp_le_i32_e64 s[28:29], v252, v102
	v_cndmask_b32_e64 v44, v203, v44, vcc
	v_add_u32_e32 v168, 57, v0
	v_cmp_le_i32_e64 vcc, v145, v102
	v_cndmask_b32_e64 v45, v203, v45, s[28:29]
	v_add_u32_e32 v252, 58, v0
	v_cmp_le_i32_e64 s[28:29], v168, v102
	v_cndmask_b32_e64 v46, v203, v46, vcc
	v_add_u32_e32 v145, 59, v0
	v_cmp_le_i32_e64 vcc, v252, v102
	v_cndmask_b32_e64 v47, v203, v47, s[28:29]
	v_cmp_le_i32_e64 s[28:29], v145, v102
	v_cndmask_b32_e64 v48, v203, v48, vcc
	s_nop 1
	v_cndmask_b32_e64 v49, v203, v49, s[28:29]

.Lat_fast2:
	ds_read_b128 v[170:173], v140 offset:45056
	ds_read_b128 v[174:177], v140 offset:45088
	ds_read_b128 v[178:181], v140 offset:45120
	ds_read_b128 v[182:185], v140 offset:45152
	ds_read_b128 v[186:189], v140 offset:45184
	ds_read_b128 v[190:193], v140 offset:45216
	ds_read_b128 v[204:207], v141 offset:45056
	ds_read_b128 v[208:211], v141 offset:45088
	s_add_i32 s23, s19, 3
	s_cmp_ge_u32 s23, s7
	s_cbranch_scc1 .Lat_noissue_f2
	global_load_dwordx4 v[90:93], v[136:137], off
	global_load_dwordx4 v[94:97], v[136:137], off offset:128
	global_load_dwordx4 v[98:101], v[138:139], off
.Lat_noissue_f2:
	s_waitcnt lgkmcnt(7)
	v_mfma_f32_32x32x16_bf16 v[50:65], v[170:173], v[66:69], v[146:161]
	ds_read_b128 v[170:173], v141 offset:45120
	s_waitcnt lgkmcnt(7)
	v_mfma_f32_32x32x16_bf16 v[50:65], v[174:177], v[70:73], v[50:65]
	ds_read_b128 v[174:177], v141 offset:45152
	s_waitcnt lgkmcnt(7)
	v_mfma_f32_32x32x16_bf16 v[50:65], v[178:181], v[74:77], v[50:65]
	ds_read_b128 v[178:181], v141 offset:45184
	s_waitcnt lgkmcnt(7)
	v_mfma_f32_32x32x16_bf16 v[50:65], v[182:185], v[78:81], v[50:65]
	ds_read_b128 v[182:185], v141 offset:45216
	s_waitcnt lgkmcnt(7)
	v_mfma_f32_32x32x16_bf16 v[50:65], v[186:189], v[82:85], v[50:65]
	s_waitcnt lgkmcnt(6)
	v_mfma_f32_32x32x16_bf16 v[50:65], v[190:193], v[86:89], v[50:65]
	ds_read_b64_tr_b16 v[186:187], v251 offset:13312
	ds_read_b64_tr_b16 v[188:189], v251 offset:14464
	ds_read_b64_tr_b16 v[190:191], v251 offset:13376
	ds_read_b64_tr_b16 v[192:193], v251 offset:14528
	s_waitcnt lgkmcnt(9)
	v_mfma_f32_32x32x16_bf16 v[34:49], v[204:207], v[66:69], v[146:161]
	ds_read_b64_tr_b16 v[204:205], v251 offset:15616
	ds_read_b64_tr_b16 v[206:207], v251 offset:16768
	s_waitcnt lgkmcnt(10)
	v_mfma_f32_32x32x16_bf16 v[34:49], v[208:211], v[70:73], v[34:49]
	ds_read_b64_tr_b16 v[208:209], v251 offset:15680
	ds_read_b64_tr_b16 v[210:211], v251 offset:16832
	s_nop 3
	s_andn2_b64 vcc, exec, s[10:11]
	s_cbranch_vccnz .Lat_fnomaskA2
	v_add_u32_e32 v0, s21, v121
	v_mov_b32_e32 v145, v0
	v_add_u32_e32 v168, 1, v0
	v_cmp_le_i32_e64 vcc, v145, v102
	v_add_u32_e32 v252, 2, v0
	v_cmp_le_i32_e64 s[28:29], v168, v102
	v_cndmask_b32_e64 v50, v203, v50, vcc
	v_add_u32_e32 v145, 3, v0
	v_cmp_le_i32_e64 vcc, v252, v102
	v_cndmask_b32_e64 v51, v203, v51, s[28:29]
	v_add_u32_e32 v168, 8, v0
	v_cmp_le_i32_e64 s[28:29], v145, v102
	v_cndmask_b32_e64 v52, v203, v52, vcc
	v_add_u32_e32 v252, 9, v0
	v_cmp_le_i32_e64 vcc, v168, v102
	v_cndmask_b32_e64 v53, v203, v53, s[28:29]
	v_add_u32_e32 v145, 10, v0
	v_cmp_le_i32_e64 s[28:29], v252, v102
	v_cndmask_b32_e64 v54, v203, v54, vcc
	v_add_u32_e32 v168, 11, v0
	v_cmp_le_i32_e64 vcc, v145, v102
	v_cndmask_b32_e64 v55, v203, v55, s[28:29]
	v_add_u32_e32 v252, 16, v0
	v_cmp_le_i32_e64 s[28:29], v168, v102
	v_cndmask_b32_e64 v56, v203, v56, vcc
	v_add_u32_e32 v145, 17, v0
	v_cmp_le_i32_e64 vcc, v252, v102
	v_cndmask_b32_e64 v57, v203, v57, s[28:29]
	v_add_u32_e32 v168, 18, v0
	v_cmp_le_i32_e64 s[28:29], v145, v102
	v_cndmask_b32_e64 v58, v203, v58, vcc
	v_add_u32_e32 v252, 19, v0
	v_cmp_le_i32_e64 vcc, v168, v102
	v_cndmask_b32_e64 v59, v203, v59, s[28:29]
	v_add_u32_e32 v145, 24, v0
	v_cmp_le_i32_e64 s[28:29], v252, v102
	v_cndmask_b32_e64 v60, v203, v60, vcc
	v_add_u32_e32 v168, 25, v0
	v_cmp_le_i32_e64 vcc, v145, v102
	v_cndmask_b32_e64 v61, v203, v61, s[28:29]
	v_add_u32_e32 v252, 26, v0
	v_cmp_le_i32_e64 s[28:29], v168, v102
	v_cndmask_b32_e64 v62, v203, v62, vcc
	v_add_u32_e32 v145, 27, v0
	v_cmp_le_i32_e64 vcc, v252, v102
	v_cndmask_b32_e64 v63, v203, v63, s[28:29]
	v_cmp_le_i32_e64 s[28:29], v145, v102
	v_cndmask_b32_e64 v64, v203, v64, vcc
	s_nop 1
	v_cndmask_b32_e64 v65, v203, v65, s[28:29]
.Lat_fnomaskA2:
	v_exp_f32_e32 v50, v50
	v_exp_f32_e32 v51, v51
	v_exp_f32_e32 v52, v52
	v_exp_f32_e32 v53, v53
	s_waitcnt lgkmcnt(11)
	v_mfma_f32_32x32x16_bf16 v[34:49], v[170:173], v[74:77], v[34:49]
	v_exp_f32_e32 v54, v54
	v_exp_f32_e32 v55, v55
	v_exp_f32_e32 v56, v56
	v_exp_f32_e32 v57, v57
	v_cvt_pk_bf16_f32 v212, v50, v51
	v_cvt_pk_bf16_f32 v213, v52, v53
	v_cvt_pk_bf16_f32 v214, v54, v55
	v_cvt_pk_bf16_f32 v215, v56, v57
	s_waitcnt lgkmcnt(10)
	v_mfma_f32_32x32x16_bf16 v[34:49], v[174:177], v[78:81], v[34:49]
	v_add_f32_e32 v163, v50, v52
	v_add_f32_e32 v237, v51, v53
	s_waitcnt lgkmcnt(6)
	v_mfma_f32_32x32x16_bf16 v[18:33], v[186:189], v[212:215], v[18:33]
	v_exp_f32_e32 v58, v58
	v_exp_f32_e32 v59, v59
	v_exp_f32_e32 v60, v60
	s_waitcnt lgkmcnt(4)
	v_mfma_f32_32x32x16_bf16 v[2:17], v[190:193], v[212:215], v[2:17]
	v_exp_f32_e32 v61, v61
	v_exp_f32_e32 v62, v62
	v_exp_f32_e32 v63, v63
	v_mfma_f32_32x32x16_bf16 v[34:49], v[178:181], v[82:85], v[34:49]
	v_exp_f32_e32 v64, v64
	v_exp_f32_e32 v65, v65
	v_add_f32_e32 v163, v163, v54
	v_add_f32_e32 v237, v237, v55
	v_mfma_f32_32x32x16_bf16 v[34:49], v[182:185], v[86:89], v[34:49]
	v_cvt_pk_bf16_f32 v216, v58, v59
	v_cvt_pk_bf16_f32 v217, v60, v61
	v_cvt_pk_bf16_f32 v218, v62, v63
	v_cvt_pk_bf16_f32 v219, v64, v65
	v_add_f32_e32 v163, v163, v56
	v_add_f32_e32 v237, v237, v57
	v_add_f32_e32 v163, v163, v58
	v_add_f32_e32 v237, v237, v59
	s_waitcnt lgkmcnt(2)
	v_mfma_f32_32x32x16_bf16 v[18:33], v[204:207], v[216:219], v[18:33]
	v_add_f32_e32 v163, v163, v60
	v_add_f32_e32 v237, v237, v61
	v_add_f32_e32 v163, v163, v62
	s_waitcnt lgkmcnt(0)
	v_mfma_f32_32x32x16_bf16 v[2:17], v[208:211], v[216:219], v[2:17]
	v_add_f32_e32 v237, v237, v63
	v_add_f32_e32 v163, v163, v64
	v_add_f32_e32 v237, v237, v65
	s_barrier
	ds_read_b64_tr_b16 v[170:171], v251 offset:17920
	ds_read_b64_tr_b16 v[172:173], v251 offset:19072
	ds_read_b64_tr_b16 v[174:175], v251 offset:17984
	ds_read_b64_tr_b16 v[176:177], v251 offset:19136
	ds_read_b64_tr_b16 v[178:179], v251 offset:20224
	ds_read_b64_tr_b16 v[180:181], v251 offset:21376
	ds_read_b64_tr_b16 v[182:183], v251 offset:20288
	ds_read_b64_tr_b16 v[184:185], v251 offset:21440
	s_add_i32 s23, s19, 3
	s_cmp_lt_u32 s23, s7
	s_cbranch_scc1 .Lat_w6_f2
	s_add_i32 s23, s19, 2
	s_cmp_lt_u32 s23, s7
	s_cbranch_scc1 .Lat_w3_f2
	s_waitcnt vmcnt(0)
	s_branch .Lat_wd_f2

.Lat_skip2:
	s_add_i32 s23, s19, 3
	s_cmp_ge_u32 s23, s7
	s_cbranch_scc1 .Lat_noissue_s2
	global_load_dwordx4 v[90:93], v[136:137], off
	global_load_dwordx4 v[94:97], v[136:137], off offset:128
	global_load_dwordx4 v[98:101], v[138:139], off

.Lat_wd_s2:
	ds_write_b128 v112, v[220:223] offset:22528
	ds_write_b128 v113, v[224:227] offset:35840
	ds_write_b128 v115, v[228:231] offset:22656

.Lat_ctl_t2:
	s_cmp_eq_u32 s25, 1
	s_cbranch_scc1 .LBB0_520
	s_branch .Lat_head0
.Lat_rareB0:
	v_max_f32_e32 v232, 0, v232
	v_exp_f32_e64 v233, -v232
	v_sub_f32_e32 v34, v34, v232
	v_sub_f32_e32 v35, v35, v232
	v_sub_f32_e32 v36, v36, v232
	v_sub_f32_e32 v37, v37, v232
	v_sub_f32_e32 v38, v38, v232
	v_sub_f32_e32 v39, v39, v232
	v_sub_f32_e32 v40, v40, v232
	v_sub_f32_e32 v41, v41, v232
	v_sub_f32_e32 v42, v42, v232
	v_sub_f32_e32 v43, v43, v232
	v_sub_f32_e32 v44, v44, v232
	v_sub_f32_e32 v45, v45, v232
	v_sub_f32_e32 v46, v46, v232
	v_sub_f32_e32 v47, v47, v232
	v_sub_f32_e32 v48, v48, v232
	v_sub_f32_e32 v49, v49, v232
	v_sub_f32_e32 v146, v146, v232
	v_mul_f32_e32 v163, v163, v233
	v_mul_f32_e32 v237, v237, v233
	v_mov_b32_e32 v147, v146
	v_mov_b32_e32 v148, v146
	v_mov_b32_e32 v149, v146
	v_mov_b32_e32 v150, v146
	v_mov_b32_e32 v151, v146
	v_mov_b32_e32 v152, v146
	v_mov_b32_e32 v153, v146
	v_mov_b32_e32 v154, v146
	v_mov_b32_e32 v155, v146
	v_mov_b32_e32 v156, v146
	v_mov_b32_e32 v157, v146
	v_mov_b32_e32 v158, v146
	v_mov_b32_e32 v159, v146
	v_mov_b32_e32 v160, v146
	v_mov_b32_e32 v161, v146
	v_mul_f32_e32 v18, v18, v233
	v_mul_f32_e32 v19, v19, v233
	v_mul_f32_e32 v20, v20, v233
	v_mul_f32_e32 v21, v21, v233
	v_mul_f32_e32 v22, v22, v233
	v_mul_f32_e32 v23, v23, v233
	v_mul_f32_e32 v24, v24, v233
	v_mul_f32_e32 v25, v25, v233
	v_mul_f32_e32 v26, v26, v233
	v_mul_f32_e32 v27, v27, v233
	v_mul_f32_e32 v28, v28, v233
	v_mul_f32_e32 v29, v29, v233
	v_mul_f32_e32 v30, v30, v233
	v_mul_f32_e32 v31, v31, v233
	v_mul_f32_e32 v32, v32, v233
	v_mul_f32_e32 v33, v33, v233
	v_mul_f32_e32 v2, v2, v233
	v_mul_f32_e32 v3, v3, v233
	v_mul_f32_e32 v4, v4, v233
	v_mul_f32_e32 v5, v5, v233
	v_mul_f32_e32 v6, v6, v233
	v_mul_f32_e32 v7, v7, v233
	v_mul_f32_e32 v8, v8, v233
	v_mul_f32_e32 v9, v9, v233
	v_mul_f32_e32 v10, v10, v233
	v_mul_f32_e32 v11, v11, v233
	v_mul_f32_e32 v12, v12, v233
	v_mul_f32_e32 v13, v13, v233
	v_mul_f32_e32 v14, v14, v233
	v_mul_f32_e32 v15, v15, v233
	v_mul_f32_e32 v16, v16, v233
	v_mul_f32_e32 v17, v17, v233
	s_nop 1
	s_branch .Lat_commonB0
.Lat_postx0:
	v_frexp_exp_i32_f32_e32 v232, v163
	v_max_i32_e32 v232, 0, v232
	v_mov_b32_e32 v233, v232
	s_nop 1
	v_permlane32_swap_b32_e32 v232, v233
	v_max_i32_e32 v232, v232, v233
	v_sub_u32_e32 v233, 0, v232
	v_cvt_f32_i32_e32 v232, v232
	v_ldexp_f32 v233, 1.0, v233
	s_nop 7
	s_nop 3
	v_sub_f32_e32 v146, v146, v232
	v_mul_f32_e32 v143, v143, v233
	v_mul_f32_e32 v18, v18, v233
	v_mul_f32_e32 v19, v19, v233
	v_mul_f32_e32 v20, v20, v233
	v_mul_f32_e32 v21, v21, v233
	v_mul_f32_e32 v22, v22, v233
	v_mul_f32_e32 v23, v23, v233
	v_mul_f32_e32 v24, v24, v233
	v_mul_f32_e32 v25, v25, v233
	v_mul_f32_e32 v26, v26, v233
	v_mul_f32_e32 v27, v27, v233
	v_mul_f32_e32 v28, v28, v233
	v_mul_f32_e32 v29, v29, v233
	v_mul_f32_e32 v30, v30, v233
	v_mul_f32_e32 v31, v31, v233
	v_mul_f32_e32 v32, v32, v233
	v_mul_f32_e32 v33, v33, v233
	v_mul_f32_e32 v2, v2, v233
	v_mul_f32_e32 v3, v3, v233
	v_mul_f32_e32 v4, v4, v233
	v_mul_f32_e32 v5, v5, v233
	v_mul_f32_e32 v6, v6, v233
	v_mul_f32_e32 v7, v7, v233
	v_mul_f32_e32 v8, v8, v233
	v_mul_f32_e32 v9, v9, v233
	v_mul_f32_e32 v10, v10, v233
	v_mul_f32_e32 v11, v11, v233
	v_mul_f32_e32 v12, v12, v233
	v_mul_f32_e32 v13, v13, v233
	v_mul_f32_e32 v14, v14, v233
	v_mul_f32_e32 v15, v15, v233
	v_mul_f32_e32 v16, v16, v233
	v_mul_f32_e32 v17, v17, v233
	v_mov_b32_e32 v147, v146
	v_mov_b32_e32 v148, v146
	v_mov_b32_e32 v149, v146
	v_mov_b32_e32 v150, v146
	v_mov_b32_e32 v151, v146
	v_mov_b32_e32 v152, v146
	v_mov_b32_e32 v153, v146
	v_mov_b32_e32 v154, v146
	v_mov_b32_e32 v155, v146
	v_mov_b32_e32 v156, v146
	v_mov_b32_e32 v157, v146
	v_mov_b32_e32 v158, v146
	v_mov_b32_e32 v159, v146
	v_mov_b32_e32 v160, v146
	v_mov_b32_e32 v161, v146
	s_nop 1
	s_branch .Lat_postdonex0

.LBB0_747:
	s_or_b64 exec, exec, s[2:3]
	v_lshl_add_u32 v178, s33, 7, v130
	v_ashrrev_i32_e32 v179, 31, v178
	v_lshlrev_b64 v[154:155], 2, v[178:179]
	v_lshl_add_u64 v[130:131], s[24:25], 0, v[154:155]
	v_lshl_add_u64 v[180:181], s[18:19], 0, v[154:155]
	v_lshl_add_u64 v[140:141], s[36:37], 0, v[154:155]
	global_load_dwordx4 v[130:133], v[130:131], off
	v_lshl_add_u64 v[138:139], s[26:27], 0, v[154:155]
	global_load_dwordx4 v[134:137], v[180:181], off
	global_load_dwordx4 v[150:153], v[140:141], off
	global_load_dwordx4 v[146:149], v[138:139], off
	v_lshl_add_u64 v[138:139], s[28:29], 0, v[154:155]
	v_lshl_add_u64 v[156:157], s[38:39], 0, v[154:155]
	v_cmp_eq_u32_e32 vcc, 15, v184
	v_cmp_lt_i32_e64 s[2:3], 13, v184
	global_load_dwordx4 v[142:145], v[138:139], off
	global_load_dwordx4 v[158:161], v[156:157], off
	v_lshl_add_u64 v[138:139], s[34:35], 0, v[154:155]
	v_lshl_add_u64 v[182:183], s[16:17], 0, v[154:155]
	v_add_u32_e32 v190, v185, v184
	v_cndmask_b32_e64 v166, v122, 0, vcc
	v_cndmask_b32_e64 v167, v122, 0, s[2:3]
	v_mov_b64_e32 v[186:187], s[12:13]
	v_cndmask_b32_e64 v191, v126, 0, vcc
	v_cndmask_b32_e64 v192, v126, 0, s[2:3]
	v_cndmask_b32_e32 v218, v118, v122, vcc
	v_cndmask_b32_e64 v219, v118, v122, s[2:3]
	v_cndmask_b32_e32 v220, v114, v126, vcc
	v_cndmask_b32_e64 v221, v114, v126, s[2:3]
	global_load_dwordx4 v[138:141], v[138:139], off
	v_cndmask_b32_e64 v193, v123, 0, vcc
	global_load_dwordx4 v[154:157], v[182:183], off
	v_cndmask_b32_e64 v207, v123, 0, s[2:3]
	v_cndmask_b32_e64 v208, v127, 0, vcc
	v_cndmask_b32_e64 v209, v127, 0, s[2:3]
	v_mad_i64_i32 v[164:165], s[44:45], v190, s82, v[186:187]
	v_cndmask_b32_e32 v222, v119, v123, vcc
	v_cndmask_b32_e64 v223, v119, v123, s[2:3]
	v_cndmask_b32_e32 v224, v115, v127, vcc
	v_cndmask_b32_e64 v225, v115, v127, s[2:3]
	v_lshlrev_b64 v[188:189], 1, v[178:179]
	v_cndmask_b32_e64 v210, v124, 0, vcc
	v_cndmask_b32_e64 v211, v124, 0, s[2:3]
	v_cndmask_b32_e32 v226, v120, v124, vcc
	v_cndmask_b32_e64 v227, v120, v124, s[2:3]
	v_lshl_add_u64 v[184:185], v[164:165], 0, v[188:189]
	v_cndmask_b32_e64 v212, v128, 0, vcc
	v_cndmask_b32_e64 v213, v128, 0, s[2:3]
	v_cndmask_b32_e64 v214, v125, 0, vcc
	v_cndmask_b32_e64 v216, v129, 0, vcc
	v_cndmask_b32_e64 v215, v125, 0, s[2:3]
	v_cndmask_b32_e64 v217, v129, 0, s[2:3]
	v_cndmask_b32_e32 v228, v116, v128, vcc
	s_waitcnt vmcnt(0)
	v_fma_f32 v122, v122, v150, v134
	v_fma_f32 v126, v126, v146, v130
	v_fma_f32 v123, v123, v151, v135
	v_fma_f32 v127, v127, v147, v131
	v_fmac_f32_dpp v122, v166, v158 row_ror:1 row_mask:0xf bank_mask:0xf
	v_fmac_f32_dpp v126, v191, v142 row_ror:1 row_mask:0xf bank_mask:0xf
	v_fma_f32 v124, v124, v152, v136
	v_fma_f32 v164, v128, v148, v132
	v_fmac_f32_dpp v122, v167, v154 row_ror:2 row_mask:0xf bank_mask:0xf
	v_fmac_f32_dpp v126, v192, v138 row_ror:2 row_mask:0xf bank_mask:0xf
	v_fmac_f32_dpp v123, v193, v159 row_ror:1 row_mask:0xf bank_mask:0xf
	v_fmac_f32_dpp v127, v208, v143 row_ror:1 row_mask:0xf bank_mask:0xf
	v_fma_f32 v165, v125, v153, v137
	v_fma_f32 v179, v129, v149, v133
	v_fmac_f32_dpp v123, v207, v155 row_ror:2 row_mask:0xf bank_mask:0xf
	v_fmac_f32_dpp v127, v209, v139 row_ror:2 row_mask:0xf bank_mask:0xf
	v_fmac_f32_dpp v124, v210, v160 row_ror:1 row_mask:0xf bank_mask:0xf
	v_fmac_f32_dpp v164, v212, v144 row_ror:1 row_mask:0xf bank_mask:0xf
	v_mul_f32_e32 v166, 0xbfb8aa3b, v122
	v_mul_f32_e32 v167, 0xbfb8aa3b, v123
	v_fmac_f32_dpp v124, v211, v156 row_ror:2 row_mask:0xf bank_mask:0xf
	v_fmac_f32_dpp v164, v213, v140 row_ror:2 row_mask:0xf bank_mask:0xf
	v_fmac_f32_dpp v165, v214, v161 row_ror:1 row_mask:0xf bank_mask:0xf
	v_fmac_f32_dpp v179, v216, v145 row_ror:1 row_mask:0xf bank_mask:0xf
	v_exp_f32_e32 v166, v166
	v_exp_f32_e32 v167, v167
	v_fmac_f32_dpp v165, v215, v157 row_ror:2 row_mask:0xf bank_mask:0xf
	v_fmac_f32_dpp v179, v217, v141 row_ror:2 row_mask:0xf bank_mask:0xf
	v_mul_f32_e32 v191, 0xbfb8aa3b, v124
	v_mul_f32_e32 v192, 0xbfb8aa3b, v165
	v_exp_f32_e32 v192, v192
	v_exp_f32_e32 v191, v191
	v_add_f32_e32 v166, 1.0, v166
	v_add_f32_e32 v167, 1.0, v167
	v_rcp_f32_e32 v166, v166
	v_rcp_f32_e32 v167, v167
	v_add_f32_e32 v192, 1.0, v192
	v_add_f32_e32 v191, 1.0, v191
	v_rcp_f32_e32 v192, v192
	v_rcp_f32_e32 v191, v191
	v_mul_f32_e32 v122, v122, v166
	v_mul_f32_e32 v123, v123, v167
	v_mul_f32_e32 v122, v126, v122
	v_mul_f32_e32 v123, v127, v123
	v_mul_f32_e32 v126, v165, v192
	v_fma_f32 v229, v118, v150, v134
	v_fma_f32 v230, v114, v146, v130
	v_mul_f32_e32 v124, v124, v191
	v_cvt_pk_bf16_f32 v122, v122, v123
	v_mul_f32_e32 v123, v179, v126
	v_fma_f32 v231, v119, v151, v135
	v_fma_f32 v232, v115, v147, v131
	v_mul_f32_e32 v124, v164, v124
	v_cvt_pk_bf16_f32 v123, v124, v123
	global_store_dwordx2 v[184:185], v[122:123], off
	v_fmac_f32_dpp v229, v218, v158 row_ror:1 row_mask:0xf bank_mask:0xf
	v_fmac_f32_dpp v230, v220, v142 row_ror:1 row_mask:0xf bank_mask:0xf
	v_fma_f32 v126, v120, v152, v136
	v_fmac_f32_dpp v229, v219, v154 row_ror:2 row_mask:0xf bank_mask:0xf
	v_fmac_f32_dpp v230, v221, v138 row_ror:2 row_mask:0xf bank_mask:0xf
	v_fmac_f32_dpp v231, v222, v159 row_ror:1 row_mask:0xf bank_mask:0xf
	v_fmac_f32_dpp v232, v224, v143 row_ror:1 row_mask:0xf bank_mask:0xf
	v_fma_f32 v127, v116, v148, v132
	v_fmac_f32_dpp v231, v223, v155 row_ror:2 row_mask:0xf bank_mask:0xf
	v_fmac_f32_dpp v232, v225, v139 row_ror:2 row_mask:0xf bank_mask:0xf
	v_cndmask_b32_e64 v124, v116, v128, s[2:3]
	v_fmac_f32_dpp v126, v226, v160 row_ror:1 row_mask:0xf bank_mask:0xf
	v_fmac_f32_dpp v127, v228, v144 row_ror:1 row_mask:0xf bank_mask:0xf
	v_fma_f32 v165, v121, v153, v137
	v_fma_f32 v166, v117, v149, v133
	v_mul_f32_e32 v122, 0xbfb8aa3b, v229
	v_fmac_f32_dpp v126, v227, v156 row_ror:2 row_mask:0xf bank_mask:0xf
	v_fmac_f32_dpp v127, v124, v140 row_ror:2 row_mask:0xf bank_mask:0xf
	v_cndmask_b32_e32 v128, v121, v125, vcc
	v_mul_f32_e32 v124, 0xbfb8aa3b, v126
	v_cndmask_b32_e64 v125, v121, v125, s[2:3]
	v_cndmask_b32_e32 v164, v117, v129, vcc
	s_nop 0
	v_fmac_f32_dpp v165, v128, v161 row_ror:1 row_mask:0xf bank_mask:0xf
	v_fmac_f32_dpp v166, v164, v145 row_ror:1 row_mask:0xf bank_mask:0xf
	v_exp_f32_e32 v122, v122
	v_mul_f32_e32 v123, 0xbfb8aa3b, v231
	v_exp_f32_e32 v124, v124
	v_cndmask_b32_e64 v129, v117, v129, s[2:3]
	s_nop 0
	v_fmac_f32_dpp v165, v125, v157 row_ror:2 row_mask:0xf bank_mask:0xf
	v_fmac_f32_dpp v166, v129, v141 row_ror:2 row_mask:0xf bank_mask:0xf
	v_exp_f32_e32 v123, v123
	v_mul_f32_e32 v125, 0xbfb8aa3b, v165
	v_exp_f32_e32 v125, v125
	v_add_f32_e32 v122, 1.0, v122
	v_add_f32_e32 v124, 1.0, v124
	v_rcp_f32_e32 v122, v122
	v_add_f32_e32 v123, 1.0, v123
	v_rcp_f32_e32 v124, v124
	v_add_f32_e32 v125, 1.0, v125
	v_rcp_f32_e32 v123, v123
	v_rcp_f32_e32 v125, v125
	v_mul_f32_e32 v122, v229, v122
	v_mul_f32_e32 v124, v126, v124
	v_mul_f32_e32 v122, v230, v122
	v_mul_f32_e32 v123, v231, v123
	v_mul_f32_e32 v126, v127, v124
	v_mul_f32_e32 v124, v165, v125
	v_mul_f32_e32 v123, v232, v123
	v_mul_f32_e32 v125, v166, v124
	v_cvt_pk_bf16_f32 v124, v122, v123
	v_add_u32_e32 v122, 16, v190
	v_mad_i64_i32 v[122:123], s[44:45], v122, s82, v[186:187]
	v_cvt_pk_bf16_f32 v125, v126, v125
	v_lshl_add_u64 v[122:123], v[122:123], 0, v[188:189]
	v_fma_f32 v126, v110, v150, v134
	v_fma_f32 v127, v106, v146, v130
	global_store_dwordx2 v[122:123], v[124:125], off
	v_cndmask_b32_e32 v124, v110, v118, vcc
	v_cndmask_b32_e32 v125, v106, v114, vcc
	v_cndmask_b32_e64 v114, v106, v114, s[2:3]
	v_fmac_f32_dpp v126, v124, v158 row_ror:1 row_mask:0xf bank_mask:0xf
	v_fmac_f32_dpp v127, v125, v142 row_ror:1 row_mask:0xf bank_mask:0xf
	v_cndmask_b32_e64 v118, v110, v118, s[2:3]
	s_nop 1
	v_fmac_f32_dpp v126, v118, v154 row_ror:2 row_mask:0xf bank_mask:0xf
	v_fmac_f32_dpp v127, v114, v138 row_ror:2 row_mask:0xf bank_mask:0xf
	v_cndmask_b32_e32 v124, v107, v115, vcc
	v_mul_f32_e32 v114, 0xbfb8aa3b, v126
	v_exp_f32_e32 v114, v114
	v_fma_f32 v125, v111, v151, v135
	v_fma_f32 v128, v107, v147, v131
	v_cndmask_b32_e32 v118, v111, v119, vcc
	v_add_f32_e32 v114, 1.0, v114
	v_rcp_f32_e32 v114, v114
	v_cndmask_b32_e64 v119, v111, v119, s[2:3]
	v_fmac_f32_dpp v125, v118, v159 row_ror:1 row_mask:0xf bank_mask:0xf
	v_fmac_f32_dpp v128, v124, v143 row_ror:1 row_mask:0xf bank_mask:0xf
	v_fma_f32 v124, v112, v152, v136
	v_mul_f32_e32 v114, v126, v114
	v_fma_f32 v126, v108, v148, v132
	v_cndmask_b32_e64 v115, v107, v115, s[2:3]
	s_nop 0
	v_fmac_f32_dpp v125, v119, v155 row_ror:2 row_mask:0xf bank_mask:0xf
	v_fmac_f32_dpp v128, v115, v139 row_ror:2 row_mask:0xf bank_mask:0xf
	v_cndmask_b32_e32 v118, v112, v120, vcc
	v_cndmask_b32_e64 v119, v112, v120, s[2:3]
	v_cndmask_b32_e32 v120, v108, v116, vcc
	s_nop 0
	v_fmac_f32_dpp v124, v118, v160 row_ror:1 row_mask:0xf bank_mask:0xf
	v_fmac_f32_dpp v126, v120, v144 row_ror:1 row_mask:0xf bank_mask:0xf
	v_mul_f32_e32 v114, v127, v114
	v_cndmask_b32_e64 v116, v108, v116, s[2:3]
	s_nop 0
	v_fmac_f32_dpp v124, v119, v156 row_ror:2 row_mask:0xf bank_mask:0xf
	v_fmac_f32_dpp v126, v116, v140 row_ror:2 row_mask:0xf bank_mask:0xf
	v_cndmask_b32_e32 v118, v113, v121, vcc
	v_cndmask_b32_e64 v119, v113, v121, s[2:3]
	v_fma_f32 v121, v113, v153, v137
	v_fma_f32 v127, v109, v149, v133
	v_mul_f32_e32 v116, 0xbfb8aa3b, v124
	v_cndmask_b32_e32 v120, v109, v117, vcc
	v_cndmask_b32_e64 v117, v109, v117, s[2:3]
	v_fmac_f32_dpp v121, v118, v161 row_ror:1 row_mask:0xf bank_mask:0xf
	v_fmac_f32_dpp v127, v120, v145 row_ror:1 row_mask:0xf bank_mask:0xf
	v_mul_f32_e32 v115, 0xbfb8aa3b, v125
	v_exp_f32_e32 v116, v116
	v_fmac_f32_dpp v121, v119, v157 row_ror:2 row_mask:0xf bank_mask:0xf
	v_fmac_f32_dpp v127, v117, v141 row_ror:2 row_mask:0xf bank_mask:0xf
	v_exp_f32_e32 v115, v115
	v_mul_f32_e32 v117, 0xbfb8aa3b, v121
	v_exp_f32_e32 v117, v117
	v_add_f32_e32 v116, 1.0, v116
	v_add_f32_e32 v115, 1.0, v115
	v_rcp_f32_e32 v116, v116
	v_add_f32_e32 v117, 1.0, v117
	v_rcp_f32_e32 v115, v115
	v_rcp_f32_e32 v117, v117
	v_mul_f32_e32 v116, v124, v116
	v_mul_f32_e32 v118, v126, v116
	v_mul_f32_e32 v115, v125, v115
	v_mul_f32_e32 v116, v121, v117
	v_mul_f32_e32 v115, v128, v115
	v_mul_f32_e32 v117, v127, v116
	v_cvt_pk_bf16_f32 v116, v114, v115
	v_add_u32_e32 v114, 32, v190
	v_mad_i64_i32 v[114:115], s[44:45], v114, s82, v[186:187]
	v_cvt_pk_bf16_f32 v117, v118, v117
	v_lshl_add_u64 v[114:115], v[114:115], 0, v[188:189]
	global_store_dwordx2 v[114:115], v[116:117], off
	v_cndmask_b32_e32 v116, v102, v110, vcc
	v_cndmask_b32_e64 v110, v102, v110, s[2:3]
	v_cndmask_b32_e32 v117, v98, v106, vcc
	v_cndmask_b32_e64 v106, v98, v106, s[2:3]
	v_fma_f32 v102, v102, v150, v134
	v_fma_f32 v98, v98, v146, v130
	s_nop 0
	v_fmac_f32_dpp v102, v116, v158 row_ror:1 row_mask:0xf bank_mask:0xf
	v_fmac_f32_dpp v98, v117, v142 row_ror:1 row_mask:0xf bank_mask:0xf
	v_cndmask_b32_e32 v116, v99, v107, vcc
	v_fmac_f32_dpp v102, v110, v154 row_ror:2 row_mask:0xf bank_mask:0xf
	v_fmac_f32_dpp v98, v106, v138 row_ror:2 row_mask:0xf bank_mask:0xf
	v_cndmask_b32_e32 v110, v103, v111, vcc
	v_mul_f32_e32 v106, 0xbfb8aa3b, v102
	v_exp_f32_e32 v106, v106
	v_cndmask_b32_e64 v111, v103, v111, s[2:3]
	v_cndmask_b32_e64 v107, v99, v107, s[2:3]
	v_fma_f32 v103, v103, v151, v135
	v_fma_f32 v99, v99, v147, v131
	v_add_f32_e32 v106, 1.0, v106
	v_fmac_f32_dpp v103, v110, v159 row_ror:1 row_mask:0xf bank_mask:0xf
	v_fmac_f32_dpp v99, v116, v143 row_ror:1 row_mask:0xf bank_mask:0xf
	v_rcp_f32_e32 v106, v106
	v_fmac_f32_dpp v103, v111, v155 row_ror:2 row_mask:0xf bank_mask:0xf
	v_fmac_f32_dpp v99, v107, v139 row_ror:2 row_mask:0xf bank_mask:0xf
	v_cndmask_b32_e32 v110, v100, v108, vcc
	v_mul_f32_e32 v107, 0xbfb8aa3b, v103
	v_exp_f32_e32 v107, v107
	v_mul_f32_e32 v102, v102, v106
	v_mul_f32_e32 v98, v98, v102
	v_cndmask_b32_e32 v106, v104, v112, vcc
	v_add_f32_e32 v102, 1.0, v107
	v_cndmask_b32_e64 v107, v104, v112, s[2:3]
	v_cndmask_b32_e64 v108, v100, v108, s[2:3]
	v_fma_f32 v104, v104, v152, v136
	v_fma_f32 v100, v100, v148, v132
	s_nop 0
	v_fmac_f32_dpp v104, v106, v160 row_ror:1 row_mask:0xf bank_mask:0xf
	v_fmac_f32_dpp v100, v110, v144 row_ror:1 row_mask:0xf bank_mask:0xf
	v_cndmask_b32_e32 v110, v101, v109, vcc
	v_fmac_f32_dpp v104, v107, v156 row_ror:2 row_mask:0xf bank_mask:0xf
	v_fmac_f32_dpp v100, v108, v140 row_ror:2 row_mask:0xf bank_mask:0xf
	v_cndmask_b32_e32 v107, v105, v113, vcc
	v_cndmask_b32_e64 v108, v105, v113, s[2:3]
	v_cndmask_b32_e64 v109, v101, v109, s[2:3]
	v_fma_f32 v105, v105, v153, v137
	v_fma_f32 v101, v101, v149, v133
	v_mul_f32_e32 v106, 0xbfb8aa3b, v104
	v_fmac_f32_dpp v105, v107, v161 row_ror:1 row_mask:0xf bank_mask:0xf
	v_fmac_f32_dpp v101, v110, v145 row_ror:1 row_mask:0xf bank_mask:0xf
	v_rcp_f32_e32 v102, v102
	v_exp_f32_e32 v106, v106
	v_fmac_f32_dpp v105, v108, v157 row_ror:2 row_mask:0xf bank_mask:0xf
	v_fmac_f32_dpp v101, v109, v141 row_ror:2 row_mask:0xf bank_mask:0xf
	v_fma_f32 v108, v91, v147, v131
	v_mul_f32_e32 v107, 0xbfb8aa3b, v105
	v_exp_f32_e32 v107, v107
	v_mul_f32_e32 v102, v103, v102
	v_add_f32_e32 v103, 1.0, v106
	v_rcp_f32_e32 v103, v103
	v_add_f32_e32 v106, 1.0, v107
	v_rcp_f32_e32 v106, v106
	v_mul_f32_e32 v99, v99, v102
	v_mul_f32_e32 v102, v104, v103
	v_mul_f32_e32 v102, v100, v102
	v_mul_f32_e32 v100, v105, v106
	v_mul_f32_e32 v101, v101, v100
	v_cvt_pk_bf16_f32 v100, v98, v99
	v_add_u32_e32 v98, 48, v190
	v_mad_i64_i32 v[98:99], s[44:45], v98, s82, v[186:187]
	v_lshl_add_u64 v[98:99], v[98:99], 0, v[188:189]
	v_fma_f32 v104, v94, v150, v134
	v_fma_f32 v105, v90, v146, v130
	v_cvt_pk_bf16_f32 v101, v102, v101
	global_store_dwordx2 v[98:99], v[100:101], off
	v_cndmask_b32_e64 v100, v94, 0, vcc
	v_cndmask_b32_e64 v102, v90, 0, vcc
	s_nop 0
	v_fmac_f32_dpp v104, v100, v158 row_ror:1 row_mask:0xf bank_mask:0xf
	v_fmac_f32_dpp v105, v102, v142 row_ror:1 row_mask:0xf bank_mask:0xf
	v_cndmask_b32_e64 v101, v94, 0, s[2:3]
	v_cndmask_b32_e64 v103, v90, 0, s[2:3]
	s_nop 0
	v_fmac_f32_dpp v104, v101, v154 row_ror:2 row_mask:0xf bank_mask:0xf
	v_fmac_f32_dpp v105, v103, v138 row_ror:2 row_mask:0xf bank_mask:0xf
	v_fma_f32 v107, v95, v151, v135
	v_mul_f32_e32 v100, 0xbfb8aa3b, v104
	v_exp_f32_e32 v100, v100
	v_cndmask_b32_e64 v101, v95, 0, vcc
	v_cndmask_b32_e64 v102, v95, 0, s[2:3]
	v_cndmask_b32_e64 v103, v91, 0, vcc
	v_add_f32_e32 v100, 1.0, v100
	v_rcp_f32_e32 v100, v100
	v_fmac_f32_dpp v107, v101, v159 row_ror:1 row_mask:0xf bank_mask:0xf
	v_fmac_f32_dpp v108, v103, v143 row_ror:1 row_mask:0xf bank_mask:0xf
	v_fma_f32 v109, v96, v152, v136
	v_fma_f32 v110, v92, v148, v132
	v_mul_f32_e32 v100, v104, v100
	v_cndmask_b32_e64 v106, v91, 0, s[2:3]
	s_nop 0
	v_fmac_f32_dpp v107, v102, v155 row_ror:2 row_mask:0xf bank_mask:0xf
	v_fmac_f32_dpp v108, v106, v139 row_ror:2 row_mask:0xf bank_mask:0xf
	v_mul_f32_e32 v100, v105, v100
	v_cndmask_b32_e64 v102, v96, 0, vcc
	v_cndmask_b32_e64 v103, v96, 0, s[2:3]
	v_cndmask_b32_e64 v104, v92, 0, vcc
	v_cndmask_b32_e64 v105, v92, 0, s[2:3]
	v_fmac_f32_dpp v109, v102, v160 row_ror:1 row_mask:0xf bank_mask:0xf
	v_fmac_f32_dpp v110, v104, v144 row_ror:1 row_mask:0xf bank_mask:0xf
	v_fma_f32 v112, v97, v153, v137
	v_fma_f32 v113, v93, v149, v133
	v_mul_f32_e32 v101, 0xbfb8aa3b, v107
	v_fmac_f32_dpp v109, v103, v156 row_ror:2 row_mask:0xf bank_mask:0xf
	v_fmac_f32_dpp v110, v105, v140 row_ror:2 row_mask:0xf bank_mask:0xf
	v_cndmask_b32_e64 v103, v97, 0, vcc
	v_mul_f32_e32 v102, 0xbfb8aa3b, v109
	v_cndmask_b32_e64 v105, v93, 0, vcc
	s_nop 0
	v_fmac_f32_dpp v112, v103, v161 row_ror:1 row_mask:0xf bank_mask:0xf
	v_fmac_f32_dpp v113, v105, v145 row_ror:1 row_mask:0xf bank_mask:0xf
	v_exp_f32_e32 v101, v101
	v_exp_f32_e32 v102, v102
	v_cndmask_b32_e64 v104, v97, 0, s[2:3]
	v_cndmask_b32_e64 v111, v93, 0, s[2:3]
	s_nop 0
	v_fmac_f32_dpp v112, v104, v157 row_ror:2 row_mask:0xf bank_mask:0xf
	v_fmac_f32_dpp v113, v111, v141 row_ror:2 row_mask:0xf bank_mask:0xf
	v_add_f32_e32 v101, 1.0, v101
	v_mul_f32_e32 v103, 0xbfb8aa3b, v112
	v_exp_f32_e32 v103, v103
	v_add_f32_e32 v102, 1.0, v102
	v_rcp_f32_e32 v101, v101
	v_rcp_f32_e32 v102, v102
	v_add_f32_e32 v103, 1.0, v103
	v_rcp_f32_e32 v103, v103
	v_mul_f32_e32 v101, v107, v101
	v_mul_f32_e32 v102, v109, v102
	v_add_u32_e32 v106, 0x80, v190
	v_mul_f32_e32 v101, v108, v101
	v_mul_f32_e32 v104, v110, v102
	v_mul_f32_e32 v102, v112, v103
	v_mul_f32_e32 v103, v113, v102
	v_cvt_pk_bf16_f32 v102, v100, v101
	v_mad_i64_i32 v[100:101], s[44:45], v106, s82, v[186:187]
	v_cvt_pk_bf16_f32 v103, v104, v103
	v_lshl_add_u64 v[100:101], v[100:101], 0, v[188:189]
	v_fma_f32 v104, v86, v150, v134
	v_fma_f32 v105, v82, v146, v130
	global_store_dwordx2 v[100:101], v[102:103], off
	v_cndmask_b32_e32 v102, v86, v94, vcc
	v_cndmask_b32_e32 v103, v82, v90, vcc
	v_cndmask_b32_e64 v90, v82, v90, s[2:3]
	v_fmac_f32_dpp v104, v102, v158 row_ror:1 row_mask:0xf bank_mask:0xf
	v_fmac_f32_dpp v105, v103, v142 row_ror:1 row_mask:0xf bank_mask:0xf
	v_cndmask_b32_e64 v94, v86, v94, s[2:3]
	s_nop 1
	v_fmac_f32_dpp v104, v94, v154 row_ror:2 row_mask:0xf bank_mask:0xf
	v_fmac_f32_dpp v105, v90, v138 row_ror:2 row_mask:0xf bank_mask:0xf
	v_cndmask_b32_e32 v102, v83, v91, vcc
	v_mul_f32_e32 v90, 0xbfb8aa3b, v104
	v_exp_f32_e32 v90, v90
	v_fma_f32 v103, v87, v151, v135
	v_fma_f32 v106, v83, v147, v131
	v_cndmask_b32_e32 v94, v87, v95, vcc
	v_add_f32_e32 v90, 1.0, v90
	v_rcp_f32_e32 v90, v90
	v_cndmask_b32_e64 v95, v87, v95, s[2:3]
	v_fmac_f32_dpp v103, v94, v159 row_ror:1 row_mask:0xf bank_mask:0xf
	v_fmac_f32_dpp v106, v102, v143 row_ror:1 row_mask:0xf bank_mask:0xf
	v_fma_f32 v102, v88, v152, v136
	v_mul_f32_e32 v90, v104, v90
	v_fma_f32 v104, v84, v148, v132
	v_cndmask_b32_e64 v91, v83, v91, s[2:3]
	s_nop 0
	v_fmac_f32_dpp v103, v95, v155 row_ror:2 row_mask:0xf bank_mask:0xf
	v_fmac_f32_dpp v106, v91, v139 row_ror:2 row_mask:0xf bank_mask:0xf
	v_cndmask_b32_e32 v94, v88, v96, vcc
	v_cndmask_b32_e64 v95, v88, v96, s[2:3]
	v_cndmask_b32_e32 v96, v84, v92, vcc
	s_nop 0
	v_fmac_f32_dpp v102, v94, v160 row_ror:1 row_mask:0xf bank_mask:0xf
	v_fmac_f32_dpp v104, v96, v144 row_ror:1 row_mask:0xf bank_mask:0xf
	v_mul_f32_e32 v90, v105, v90
	v_cndmask_b32_e64 v92, v84, v92, s[2:3]
	s_nop 0
	v_fmac_f32_dpp v102, v95, v156 row_ror:2 row_mask:0xf bank_mask:0xf
	v_fmac_f32_dpp v104, v92, v140 row_ror:2 row_mask:0xf bank_mask:0xf
	v_cndmask_b32_e32 v94, v89, v97, vcc
	v_cndmask_b32_e64 v95, v89, v97, s[2:3]
	v_fma_f32 v97, v89, v153, v137
	v_fma_f32 v105, v85, v149, v133
	v_mul_f32_e32 v91, 0xbfb8aa3b, v103
	v_mul_f32_e32 v92, 0xbfb8aa3b, v102
	v_cndmask_b32_e32 v96, v85, v93, vcc
	v_cndmask_b32_e64 v93, v85, v93, s[2:3]
	v_fmac_f32_dpp v97, v94, v161 row_ror:1 row_mask:0xf bank_mask:0xf
	v_fmac_f32_dpp v105, v96, v145 row_ror:1 row_mask:0xf bank_mask:0xf
	v_exp_f32_e32 v91, v91
	v_exp_f32_e32 v92, v92
	v_fmac_f32_dpp v97, v95, v157 row_ror:2 row_mask:0xf bank_mask:0xf
	v_fmac_f32_dpp v105, v93, v141 row_ror:2 row_mask:0xf bank_mask:0xf
	v_fma_f32 v94, v75, v147, v131
	v_mul_f32_e32 v93, 0xbfb8aa3b, v97
	v_exp_f32_e32 v93, v93
	v_add_f32_e32 v91, 1.0, v91
	v_add_f32_e32 v92, 1.0, v92
	v_rcp_f32_e32 v91, v91
	v_rcp_f32_e32 v92, v92
	v_add_f32_e32 v93, 1.0, v93
	v_rcp_f32_e32 v93, v93
	v_mul_f32_e32 v91, v103, v91
	v_mul_f32_e32 v92, v102, v92
	v_mul_f32_e32 v91, v106, v91
	v_mul_f32_e32 v92, v104, v92
	v_mul_f32_e32 v93, v97, v93
	v_mul_f32_e32 v93, v105, v93
	v_cvt_pk_bf16_f32 v90, v90, v91
	v_cvt_pk_bf16_f32 v91, v92, v93
	v_add_u32_e32 v92, 0x90, v190
	v_mad_i64_i32 v[92:93], s[44:45], v92, s82, v[186:187]
	v_lshl_add_u64 v[102:103], v[92:93], 0, v[188:189]
	v_fma_f32 v92, v78, v150, v134
	v_fma_f32 v93, v74, v146, v130
	global_store_dwordx2 v[102:103], v[90:91], off
	v_cndmask_b32_e32 v90, v78, v86, vcc
	v_cndmask_b32_e32 v91, v74, v82, vcc
	v_cndmask_b32_e64 v82, v74, v82, s[2:3]
	v_fmac_f32_dpp v92, v90, v158 row_ror:1 row_mask:0xf bank_mask:0xf
	v_fmac_f32_dpp v93, v91, v142 row_ror:1 row_mask:0xf bank_mask:0xf
	v_cndmask_b32_e64 v86, v78, v86, s[2:3]
	s_nop 1
	v_fmac_f32_dpp v92, v86, v154 row_ror:2 row_mask:0xf bank_mask:0xf
	v_fmac_f32_dpp v93, v82, v138 row_ror:2 row_mask:0xf bank_mask:0xf
	v_cndmask_b32_e32 v90, v75, v83, vcc
	v_mul_f32_e32 v82, 0xbfb8aa3b, v92
	v_exp_f32_e32 v82, v82
	v_fma_f32 v91, v79, v151, v135
	v_cndmask_b32_e32 v86, v79, v87, vcc
	v_cndmask_b32_e64 v87, v79, v87, s[2:3]
	v_add_f32_e32 v82, 1.0, v82
	v_rcp_f32_e32 v82, v82
	v_fmac_f32_dpp v91, v86, v159 row_ror:1 row_mask:0xf bank_mask:0xf
	v_fmac_f32_dpp v94, v90, v143 row_ror:1 row_mask:0xf bank_mask:0xf
	v_fma_f32 v90, v80, v152, v136
	v_cndmask_b32_e64 v83, v75, v83, s[2:3]
	v_mul_f32_e32 v82, v92, v82
	v_fma_f32 v92, v76, v148, v132
	v_fmac_f32_dpp v91, v87, v155 row_ror:2 row_mask:0xf bank_mask:0xf
	v_fmac_f32_dpp v94, v83, v139 row_ror:2 row_mask:0xf bank_mask:0xf
	v_cndmask_b32_e32 v86, v80, v88, vcc
	v_cndmask_b32_e64 v87, v80, v88, s[2:3]
	v_cndmask_b32_e32 v88, v76, v84, vcc
	s_nop 0
	v_fmac_f32_dpp v90, v86, v160 row_ror:1 row_mask:0xf bank_mask:0xf
	v_fmac_f32_dpp v92, v88, v144 row_ror:1 row_mask:0xf bank_mask:0xf
	v_mul_f32_e32 v82, v93, v82
	v_cndmask_b32_e64 v84, v76, v84, s[2:3]
	s_nop 0
	v_fmac_f32_dpp v90, v87, v156 row_ror:2 row_mask:0xf bank_mask:0xf
	v_fmac_f32_dpp v92, v84, v140 row_ror:2 row_mask:0xf bank_mask:0xf
	v_cndmask_b32_e32 v86, v81, v89, vcc
	v_cndmask_b32_e64 v87, v81, v89, s[2:3]
	v_fma_f32 v89, v81, v153, v137
	v_fma_f32 v93, v77, v149, v133
	v_mul_f32_e32 v83, 0xbfb8aa3b, v91
	v_mul_f32_e32 v84, 0xbfb8aa3b, v90
	v_cndmask_b32_e32 v88, v77, v85, vcc
	v_cndmask_b32_e64 v85, v77, v85, s[2:3]
	v_fmac_f32_dpp v89, v86, v161 row_ror:1 row_mask:0xf bank_mask:0xf
	v_fmac_f32_dpp v93, v88, v145 row_ror:1 row_mask:0xf bank_mask:0xf
	v_exp_f32_e32 v83, v83
	v_exp_f32_e32 v84, v84
	v_fmac_f32_dpp v89, v87, v157 row_ror:2 row_mask:0xf bank_mask:0xf
	v_fmac_f32_dpp v93, v85, v141 row_ror:2 row_mask:0xf bank_mask:0xf
	v_fmac_f32_e32 v137, v73, v153
	v_mul_f32_e32 v85, 0xbfb8aa3b, v89
	v_exp_f32_e32 v85, v85
	v_add_f32_e32 v83, 1.0, v83
	v_add_f32_e32 v84, 1.0, v84
	v_rcp_f32_e32 v83, v83
	v_rcp_f32_e32 v84, v84
	v_add_f32_e32 v85, 1.0, v85
	v_rcp_f32_e32 v85, v85
	v_mul_f32_e32 v83, v91, v83
	v_mul_f32_e32 v84, v90, v84
	v_mul_f32_e32 v83, v94, v83
	v_mul_f32_e32 v84, v92, v84
	v_mul_f32_e32 v85, v89, v85
	v_mul_f32_e32 v85, v93, v85
	v_cvt_pk_bf16_f32 v82, v82, v83
	v_cvt_pk_bf16_f32 v83, v84, v85
	v_add_u32_e32 v84, 0xa0, v190
	v_mad_i64_i32 v[84:85], s[44:45], v84, s82, v[186:187]
	v_lshl_add_u64 v[104:105], v[84:85], 0, v[188:189]
	global_store_dwordx2 v[104:105], v[82:83], off
	v_cndmask_b32_e32 v82, v70, v78, vcc
	v_cndmask_b32_e64 v78, v70, v78, s[2:3]
	v_cndmask_b32_e32 v83, v66, v74, vcc
	v_cndmask_b32_e64 v74, v66, v74, s[2:3]
	v_fma_f32 v70, v70, v150, v134
	v_fma_f32 v66, v66, v146, v130
	s_nop 0
	v_fmac_f32_dpp v70, v82, v158 row_ror:1 row_mask:0xf bank_mask:0xf
	v_fmac_f32_dpp v66, v83, v142 row_ror:1 row_mask:0xf bank_mask:0xf
	v_cndmask_b32_e32 v82, v67, v75, vcc
	v_fmac_f32_dpp v70, v78, v154 row_ror:2 row_mask:0xf bank_mask:0xf
	v_fmac_f32_dpp v66, v74, v138 row_ror:2 row_mask:0xf bank_mask:0xf
	v_cndmask_b32_e32 v78, v71, v79, vcc
	v_mul_f32_e32 v74, 0xbfb8aa3b, v70
	v_exp_f32_e32 v74, v74
	v_cndmask_b32_e64 v79, v71, v79, s[2:3]
	v_cndmask_b32_e64 v75, v67, v75, s[2:3]
	v_fma_f32 v71, v71, v151, v135
	v_fma_f32 v67, v67, v147, v131
	v_add_f32_e32 v74, 1.0, v74
	v_fmac_f32_dpp v71, v78, v159 row_ror:1 row_mask:0xf bank_mask:0xf
	v_fmac_f32_dpp v67, v82, v143 row_ror:1 row_mask:0xf bank_mask:0xf
	v_rcp_f32_e32 v74, v74
	v_fmac_f32_dpp v71, v79, v155 row_ror:2 row_mask:0xf bank_mask:0xf
	v_fmac_f32_dpp v67, v75, v139 row_ror:2 row_mask:0xf bank_mask:0xf
	v_cndmask_b32_e32 v78, v68, v76, vcc
	v_mul_f32_e32 v75, 0xbfb8aa3b, v71
	v_exp_f32_e32 v75, v75
	v_mul_f32_e32 v70, v70, v74
	v_mul_f32_e32 v66, v66, v70
	v_cndmask_b32_e32 v74, v72, v80, vcc
	v_add_f32_e32 v70, 1.0, v75
	v_cndmask_b32_e64 v75, v72, v80, s[2:3]
	v_cndmask_b32_e64 v76, v68, v76, s[2:3]
	v_fma_f32 v72, v72, v152, v136
	v_fma_f32 v68, v68, v148, v132
	s_nop 0
	v_fmac_f32_dpp v72, v74, v160 row_ror:1 row_mask:0xf bank_mask:0xf
	v_fmac_f32_dpp v68, v78, v144 row_ror:1 row_mask:0xf bank_mask:0xf
	v_fmac_f32_e32 v133, v69, v149
	v_fmac_f32_dpp v72, v75, v156 row_ror:2 row_mask:0xf bank_mask:0xf
	v_fmac_f32_dpp v68, v76, v140 row_ror:2 row_mask:0xf bank_mask:0xf
	v_cndmask_b32_e32 v75, v73, v81, vcc
	v_mul_f32_e32 v74, 0xbfb8aa3b, v72
	v_cndmask_b32_e32 v78, v69, v77, vcc
	s_nop 0
	v_fmac_f32_dpp v137, v75, v161 row_ror:1 row_mask:0xf bank_mask:0xf
	v_fmac_f32_dpp v133, v78, v145 row_ror:1 row_mask:0xf bank_mask:0xf
	v_rcp_f32_e32 v70, v70
	v_exp_f32_e32 v74, v74
	v_cndmask_b32_e64 v76, v73, v81, s[2:3]
	v_cndmask_b32_e64 v77, v69, v77, s[2:3]
	s_nop 0
	v_fmac_f32_dpp v137, v76, v157 row_ror:2 row_mask:0xf bank_mask:0xf
	v_fmac_f32_dpp v133, v77, v141 row_ror:2 row_mask:0xf bank_mask:0xf
	v_mul_f32_e32 v70, v71, v70
	v_mul_f32_e32 v69, 0xbfb8aa3b, v137
	v_exp_f32_e32 v69, v69
	v_add_f32_e32 v71, 1.0, v74
	v_rcp_f32_e32 v71, v71
	v_mul_f32_e32 v67, v67, v70
	v_add_f32_e32 v69, 1.0, v69
	v_rcp_f32_e32 v69, v69
	v_mul_f32_e32 v70, v72, v71
	v_mul_f32_e32 v68, v68, v70
	v_cvt_pk_bf16_f32 v66, v66, v67
	v_mul_f32_e32 v69, v137, v69
	v_mul_f32_e32 v69, v133, v69
	v_cvt_pk_bf16_f32 v67, v68, v69
	v_add_u32_e32 v68, 0xb0, v190
	v_mad_i64_i32 v[68:69], s[44:45], v68, s82, v[186:187]
	v_lshl_add_u64 v[106:107], v[68:69], 0, v[188:189]
	global_store_dwordx2 v[106:107], v[66:67], off
	v_or_b32_e32 v66, 4, v178
	v_ashrrev_i32_e32 v67, 31, v66
	v_lshlrev_b64 v[86:87], 2, v[66:67]
	v_lshl_add_u64 v[66:67], s[24:25], 0, v[86:87]
	v_lshl_add_u64 v[70:71], s[26:27], 0, v[86:87]
	v_lshl_add_u64 v[72:73], s[28:29], 0, v[86:87]
	v_lshl_add_u64 v[82:83], s[34:35], 0, v[86:87]
	global_load_dwordx4 v[66:69], v[66:67], off
	s_nop 0
	global_load_dwordx4 v[78:81], v[70:71], off
	global_load_dwordx4 v[74:77], v[72:73], off
	v_lshl_add_u64 v[88:89], s[36:37], 0, v[86:87]
	global_load_dwordx4 v[70:73], v[180:181], off offset:16
	s_nop 0
	global_load_dwordx4 v[82:85], v[82:83], off
	s_nop 0
	global_load_dwordx4 v[94:97], v[88:89], off
	v_lshl_add_u64 v[86:87], s[38:39], 0, v[86:87]
	global_load_dwordx4 v[90:93], v[86:87], off
	s_nop 0
	global_load_dwordx4 v[86:89], v[182:183], off offset:16
	v_cndmask_b32_e64 v108, v58, 0, vcc
	v_cndmask_b32_e64 v110, v62, 0, vcc
	v_cndmask_b32_e64 v109, v58, 0, s[2:3]
	v_cndmask_b32_e64 v111, v62, 0, s[2:3]
	v_cndmask_b32_e64 v116, v63, 0, s[2:3]
	v_cndmask_b32_e64 v120, v65, 0, s[2:3]
	s_waitcnt vmcnt(0)
	v_fma_f32 v113, v62, v78, v66
	v_fma_f32 v118, v63, v79, v67
	v_fma_f32 v119, v64, v80, v68
	v_fma_f32 v124, v65, v81, v69
	v_fma_f32 v112, v58, v94, v70
	s_nop 1
	v_fmac_f32_dpp v112, v108, v90 row_ror:1 row_mask:0xf bank_mask:0xf
	v_fmac_f32_dpp v113, v110, v74 row_ror:1 row_mask:0xf bank_mask:0xf
	v_fma_f32 v117, v59, v95, v71
	v_fmac_f32_dpp v112, v109, v86 row_ror:2 row_mask:0xf bank_mask:0xf
	v_fmac_f32_dpp v113, v111, v82 row_ror:2 row_mask:0xf bank_mask:0xf
	v_cndmask_b32_e64 v109, v59, 0, vcc
	v_mul_f32_e32 v108, 0xbfb8aa3b, v112
	v_exp_f32_e32 v108, v108
	v_cndmask_b32_e64 v111, v63, 0, vcc
	s_nop 0
	v_fmac_f32_dpp v117, v109, v91 row_ror:1 row_mask:0xf bank_mask:0xf
	v_fmac_f32_dpp v118, v111, v75 row_ror:1 row_mask:0xf bank_mask:0xf
	v_cndmask_b32_e64 v110, v59, 0, s[2:3]
	v_add_f32_e32 v108, 1.0, v108
	v_rcp_f32_e32 v108, v108
	v_fmac_f32_dpp v117, v110, v87 row_ror:2 row_mask:0xf bank_mask:0xf
	v_fmac_f32_dpp v118, v116, v83 row_ror:2 row_mask:0xf bank_mask:0xf
	v_fma_f32 v116, v60, v96, v72
	v_cndmask_b32_e64 v110, v60, 0, vcc
	v_mul_f32_e32 v108, v112, v108
	v_mul_f32_e32 v108, v113, v108
	v_cndmask_b32_e64 v111, v60, 0, s[2:3]
	v_cndmask_b32_e64 v112, v64, 0, vcc
	v_cndmask_b32_e64 v113, v64, 0, s[2:3]
	v_fmac_f32_dpp v116, v110, v92 row_ror:1 row_mask:0xf bank_mask:0xf
	v_fmac_f32_dpp v119, v112, v76 row_ror:1 row_mask:0xf bank_mask:0xf
	v_fma_f32 v121, v61, v97, v73
	v_fmac_f32_dpp v116, v111, v88 row_ror:2 row_mask:0xf bank_mask:0xf
	v_fmac_f32_dpp v119, v113, v84 row_ror:2 row_mask:0xf bank_mask:0xf
	v_cndmask_b32_e64 v111, v61, 0, vcc
	v_cndmask_b32_e64 v113, v65, 0, vcc
	s_nop 0
	v_fmac_f32_dpp v121, v111, v93 row_ror:1 row_mask:0xf bank_mask:0xf
	v_fmac_f32_dpp v124, v113, v77 row_ror:1 row_mask:0xf bank_mask:0xf
	v_mul_f32_e32 v109, 0xbfb8aa3b, v117
	v_mul_f32_e32 v110, 0xbfb8aa3b, v116
	v_cndmask_b32_e64 v112, v61, 0, s[2:3]
	s_nop 1
	v_fmac_f32_dpp v121, v112, v89 row_ror:2 row_mask:0xf bank_mask:0xf
	v_fmac_f32_dpp v124, v120, v85 row_ror:2 row_mask:0xf bank_mask:0xf
	v_exp_f32_e32 v109, v109
	v_mul_f32_e32 v111, 0xbfb8aa3b, v121
	v_exp_f32_e32 v110, v110
	v_exp_f32_e32 v111, v111
	v_add_f32_e32 v109, 1.0, v109
	v_rcp_f32_e32 v109, v109
	v_add_f32_e32 v110, 1.0, v110
	v_add_f32_e32 v111, 1.0, v111
	v_rcp_f32_e32 v110, v110
	v_rcp_f32_e32 v111, v111
	v_mul_f32_e32 v109, v117, v109
	v_mul_f32_e32 v109, v118, v109
	v_mul_f32_e32 v110, v116, v110
	v_mul_f32_e32 v111, v121, v111
	v_mul_f32_e32 v110, v119, v110
	v_mul_f32_e32 v111, v124, v111
	v_cvt_pk_bf16_f32 v108, v108, v109
	v_cvt_pk_bf16_f32 v109, v110, v111
	v_fma_f32 v110, v54, v94, v70
	v_fma_f32 v111, v50, v78, v66
	global_store_dwordx2 v[184:185], v[108:109], off offset:8
	v_cndmask_b32_e32 v108, v54, v58, vcc
	v_cndmask_b32_e64 v58, v54, v58, s[2:3]
	v_cndmask_b32_e32 v109, v50, v62, vcc
	s_nop 0
	v_fmac_f32_dpp v110, v108, v90 row_ror:1 row_mask:0xf bank_mask:0xf
	v_fmac_f32_dpp v111, v109, v74 row_ror:1 row_mask:0xf bank_mask:0xf
	v_cndmask_b32_e64 v62, v50, v62, s[2:3]
	s_nop 0
	v_fmac_f32_dpp v110, v58, v86 row_ror:2 row_mask:0xf bank_mask:0xf
	v_fmac_f32_dpp v111, v62, v82 row_ror:2 row_mask:0xf bank_mask:0xf
	v_cndmask_b32_e32 v108, v51, v63, vcc
	v_mul_f32_e32 v58, 0xbfb8aa3b, v110
	v_exp_f32_e32 v58, v58
	v_fma_f32 v109, v55, v95, v71
	v_fma_f32 v112, v51, v79, v67
	v_cndmask_b32_e32 v62, v55, v59, vcc
	v_add_f32_e32 v58, 1.0, v58
	v_rcp_f32_e32 v58, v58
	v_cndmask_b32_e64 v63, v51, v63, s[2:3]
	v_fmac_f32_dpp v109, v62, v91 row_ror:1 row_mask:0xf bank_mask:0xf
	v_fmac_f32_dpp v112, v108, v75 row_ror:1 row_mask:0xf bank_mask:0xf
	v_fma_f32 v108, v56, v96, v72
	v_mul_f32_e32 v58, v110, v58
	v_fma_f32 v110, v52, v80, v68
	v_cndmask_b32_e64 v59, v55, v59, s[2:3]
	s_nop 1
	v_fmac_f32_dpp v109, v59, v87 row_ror:2 row_mask:0xf bank_mask:0xf
	v_fmac_f32_dpp v112, v63, v83 row_ror:2 row_mask:0xf bank_mask:0xf
	v_cndmask_b32_e32 v62, v56, v60, vcc
	v_cndmask_b32_e32 v63, v52, v64, vcc
	v_cndmask_b32_e64 v64, v52, v64, s[2:3]
	v_fmac_f32_dpp v108, v62, v92 row_ror:1 row_mask:0xf bank_mask:0xf
	v_fmac_f32_dpp v110, v63, v76 row_ror:1 row_mask:0xf bank_mask:0xf
	v_mul_f32_e32 v58, v111, v58
	v_cndmask_b32_e64 v60, v56, v60, s[2:3]
	s_nop 1
	v_fmac_f32_dpp v108, v60, v88 row_ror:2 row_mask:0xf bank_mask:0xf
	v_fmac_f32_dpp v110, v64, v84 row_ror:2 row_mask:0xf bank_mask:0xf
	v_cndmask_b32_e32 v63, v53, v65, vcc
	v_cndmask_b32_e64 v64, v53, v65, s[2:3]
	v_fma_f32 v65, v57, v97, v73
	v_fma_f32 v111, v53, v81, v69
	v_cndmask_b32_e32 v62, v57, v61, vcc
	v_cndmask_b32_e64 v61, v57, v61, s[2:3]
	s_nop 0
	v_fmac_f32_dpp v65, v62, v93 row_ror:1 row_mask:0xf bank_mask:0xf
	v_fmac_f32_dpp v111, v63, v77 row_ror:1 row_mask:0xf bank_mask:0xf
	v_mul_f32_e32 v59, 0xbfb8aa3b, v109
	v_mul_f32_e32 v60, 0xbfb8aa3b, v108
	v_fmac_f32_dpp v65, v61, v89 row_ror:2 row_mask:0xf bank_mask:0xf
	v_fmac_f32_dpp v111, v64, v85 row_ror:2 row_mask:0xf bank_mask:0xf
	v_exp_f32_e32 v59, v59
	v_mul_f32_e32 v61, 0xbfb8aa3b, v65
	v_exp_f32_e32 v60, v60
	v_exp_f32_e32 v61, v61
	v_add_f32_e32 v59, 1.0, v59
	v_rcp_f32_e32 v59, v59
	v_add_f32_e32 v60, 1.0, v60
	v_add_f32_e32 v61, 1.0, v61
	v_rcp_f32_e32 v60, v60
	v_rcp_f32_e32 v61, v61
	v_mul_f32_e32 v59, v109, v59
	v_mul_f32_e32 v59, v112, v59
	v_mul_f32_e32 v60, v108, v60
	v_mul_f32_e32 v61, v65, v61
	v_mul_f32_e32 v60, v110, v60
	v_mul_f32_e32 v61, v111, v61
	v_cvt_pk_bf16_f32 v58, v58, v59
	v_cvt_pk_bf16_f32 v59, v60, v61
	v_fma_f32 v60, v46, v94, v70
	v_fma_f32 v61, v42, v78, v66
	global_store_dwordx2 v[122:123], v[58:59], off offset:8
	v_cndmask_b32_e32 v58, v46, v54, vcc
	v_cndmask_b32_e32 v59, v42, v50, vcc
	v_cndmask_b32_e64 v50, v42, v50, s[2:3]
	v_fmac_f32_dpp v60, v58, v90 row_ror:1 row_mask:0xf bank_mask:0xf
	v_fmac_f32_dpp v61, v59, v74 row_ror:1 row_mask:0xf bank_mask:0xf
	v_cndmask_b32_e64 v54, v46, v54, s[2:3]
	s_nop 1
	v_fmac_f32_dpp v60, v54, v86 row_ror:2 row_mask:0xf bank_mask:0xf
	v_fmac_f32_dpp v61, v50, v82 row_ror:2 row_mask:0xf bank_mask:0xf
	v_cndmask_b32_e32 v58, v43, v51, vcc
	v_mul_f32_e32 v50, 0xbfb8aa3b, v60
	v_exp_f32_e32 v50, v50
	v_fma_f32 v59, v47, v95, v71
	v_fma_f32 v62, v43, v79, v67
	v_cndmask_b32_e32 v54, v47, v55, vcc
	v_add_f32_e32 v50, 1.0, v50
	v_rcp_f32_e32 v50, v50
	v_cndmask_b32_e64 v55, v47, v55, s[2:3]
	v_fmac_f32_dpp v59, v54, v91 row_ror:1 row_mask:0xf bank_mask:0xf
	v_fmac_f32_dpp v62, v58, v75 row_ror:1 row_mask:0xf bank_mask:0xf
	v_fma_f32 v58, v48, v96, v72
	v_mul_f32_e32 v50, v60, v50
	v_fma_f32 v60, v44, v80, v68
	v_cndmask_b32_e64 v51, v43, v51, s[2:3]
	s_nop 0
	v_fmac_f32_dpp v59, v55, v87 row_ror:2 row_mask:0xf bank_mask:0xf
	v_fmac_f32_dpp v62, v51, v83 row_ror:2 row_mask:0xf bank_mask:0xf
	v_cndmask_b32_e32 v54, v48, v56, vcc
	v_cndmask_b32_e64 v55, v48, v56, s[2:3]
	v_cndmask_b32_e32 v56, v44, v52, vcc
	s_nop 0
	v_fmac_f32_dpp v58, v54, v92 row_ror:1 row_mask:0xf bank_mask:0xf
	v_fmac_f32_dpp v60, v56, v76 row_ror:1 row_mask:0xf bank_mask:0xf
	v_mul_f32_e32 v50, v61, v50
	v_cndmask_b32_e64 v52, v44, v52, s[2:3]
	s_nop 0
	v_fmac_f32_dpp v58, v55, v88 row_ror:2 row_mask:0xf bank_mask:0xf
	v_fmac_f32_dpp v60, v52, v84 row_ror:2 row_mask:0xf bank_mask:0xf
	v_cndmask_b32_e32 v54, v49, v57, vcc
	v_cndmask_b32_e64 v55, v49, v57, s[2:3]
	v_fma_f32 v57, v49, v97, v73
	v_fma_f32 v61, v45, v81, v69
	v_mul_f32_e32 v51, 0xbfb8aa3b, v59
	v_cndmask_b32_e32 v56, v45, v53, vcc
	v_cndmask_b32_e64 v53, v45, v53, s[2:3]
	v_fmac_f32_dpp v57, v54, v93 row_ror:1 row_mask:0xf bank_mask:0xf
	v_fmac_f32_dpp v61, v56, v77 row_ror:1 row_mask:0xf bank_mask:0xf
	v_exp_f32_e32 v51, v51
	v_mul_f32_e32 v52, 0xbfb8aa3b, v58
	v_fmac_f32_dpp v57, v55, v89 row_ror:2 row_mask:0xf bank_mask:0xf
	v_fmac_f32_dpp v61, v53, v85 row_ror:2 row_mask:0xf bank_mask:0xf
	v_exp_f32_e32 v52, v52
	v_mul_f32_e32 v53, 0xbfb8aa3b, v57
	v_exp_f32_e32 v53, v53
	v_add_f32_e32 v51, 1.0, v51
	v_rcp_f32_e32 v51, v51
	v_add_f32_e32 v52, 1.0, v52
	v_add_f32_e32 v53, 1.0, v53
	v_rcp_f32_e32 v52, v52
	v_rcp_f32_e32 v53, v53
	v_mul_f32_e32 v51, v59, v51
	v_mul_f32_e32 v51, v62, v51
	v_mul_f32_e32 v52, v58, v52
	v_mul_f32_e32 v53, v57, v53
	v_mul_f32_e32 v52, v60, v52
	v_mul_f32_e32 v53, v61, v53
	v_cvt_pk_bf16_f32 v50, v50, v51
	v_cvt_pk_bf16_f32 v51, v52, v53
	global_store_dwordx2 v[114:115], v[50:51], off offset:8
	v_cndmask_b32_e32 v50, v38, v46, vcc
	v_cndmask_b32_e64 v46, v38, v46, s[2:3]
	v_cndmask_b32_e32 v51, v34, v42, vcc
	v_cndmask_b32_e64 v42, v34, v42, s[2:3]
	v_fma_f32 v38, v38, v94, v70
	v_fma_f32 v34, v34, v78, v66
	s_nop 0
	v_fmac_f32_dpp v38, v50, v90 row_ror:1 row_mask:0xf bank_mask:0xf
	v_fmac_f32_dpp v34, v51, v74 row_ror:1 row_mask:0xf bank_mask:0xf
	v_cndmask_b32_e32 v50, v35, v43, vcc
	v_fmac_f32_dpp v38, v46, v86 row_ror:2 row_mask:0xf bank_mask:0xf
	v_fmac_f32_dpp v34, v42, v82 row_ror:2 row_mask:0xf bank_mask:0xf
	v_cndmask_b32_e32 v46, v39, v47, vcc
	v_mul_f32_e32 v42, 0xbfb8aa3b, v38
	v_exp_f32_e32 v42, v42
	v_cndmask_b32_e64 v47, v39, v47, s[2:3]
	v_cndmask_b32_e64 v43, v35, v43, s[2:3]
	v_fma_f32 v39, v39, v95, v71
	v_fma_f32 v35, v35, v79, v67
	v_add_f32_e32 v42, 1.0, v42
	v_fmac_f32_dpp v39, v46, v91 row_ror:1 row_mask:0xf bank_mask:0xf
	v_fmac_f32_dpp v35, v50, v75 row_ror:1 row_mask:0xf bank_mask:0xf
	v_rcp_f32_e32 v42, v42
	v_fmac_f32_dpp v39, v47, v87 row_ror:2 row_mask:0xf bank_mask:0xf
	v_fmac_f32_dpp v35, v43, v83 row_ror:2 row_mask:0xf bank_mask:0xf
	v_cndmask_b32_e32 v46, v36, v44, vcc
	v_mul_f32_e32 v43, 0xbfb8aa3b, v39
	v_exp_f32_e32 v43, v43
	v_mul_f32_e32 v38, v38, v42
	v_mul_f32_e32 v34, v34, v38
	v_cndmask_b32_e32 v42, v40, v48, vcc
	v_add_f32_e32 v38, 1.0, v43
	v_cndmask_b32_e64 v43, v40, v48, s[2:3]
	v_cndmask_b32_e64 v44, v36, v44, s[2:3]
	v_fma_f32 v40, v40, v96, v72
	v_fma_f32 v36, v36, v80, v68
	s_nop 0
	v_fmac_f32_dpp v40, v42, v92 row_ror:1 row_mask:0xf bank_mask:0xf
	v_fmac_f32_dpp v36, v46, v76 row_ror:1 row_mask:0xf bank_mask:0xf
	v_cndmask_b32_e32 v46, v37, v45, vcc
	v_fmac_f32_dpp v40, v43, v88 row_ror:2 row_mask:0xf bank_mask:0xf
	v_fmac_f32_dpp v36, v44, v84 row_ror:2 row_mask:0xf bank_mask:0xf
	v_cndmask_b32_e32 v43, v41, v49, vcc
	v_cndmask_b32_e64 v44, v41, v49, s[2:3]
	v_cndmask_b32_e64 v45, v37, v45, s[2:3]
	v_fma_f32 v41, v41, v97, v73
	v_fma_f32 v37, v37, v81, v69
	v_mul_f32_e32 v42, 0xbfb8aa3b, v40
	v_fmac_f32_dpp v41, v43, v93 row_ror:1 row_mask:0xf bank_mask:0xf
	v_fmac_f32_dpp v37, v46, v77 row_ror:1 row_mask:0xf bank_mask:0xf
	v_rcp_f32_e32 v38, v38
	v_exp_f32_e32 v42, v42
	v_fmac_f32_dpp v41, v44, v89 row_ror:2 row_mask:0xf bank_mask:0xf
	v_fmac_f32_dpp v37, v45, v85 row_ror:2 row_mask:0xf bank_mask:0xf
	v_fma_f32 v45, v33, v97, v73
	v_mul_f32_e32 v43, 0xbfb8aa3b, v41
	v_exp_f32_e32 v43, v43
	v_mul_f32_e32 v38, v39, v38
	v_add_f32_e32 v39, 1.0, v42
	v_rcp_f32_e32 v39, v39
	v_add_f32_e32 v42, 1.0, v43
	v_rcp_f32_e32 v42, v42
	v_mul_f32_e32 v35, v35, v38
	v_mul_f32_e32 v38, v40, v39
	v_mul_f32_e32 v36, v36, v38
	v_mul_f32_e32 v38, v41, v42
	v_mul_f32_e32 v37, v37, v38
	v_cvt_pk_bf16_f32 v34, v34, v35
	v_fma_f32 v38, v30, v94, v70
	v_fma_f32 v39, v26, v78, v66
	v_cvt_pk_bf16_f32 v35, v36, v37
	global_store_dwordx2 v[98:99], v[34:35], off offset:8
	v_cndmask_b32_e64 v34, v30, 0, vcc
	v_cndmask_b32_e64 v36, v26, 0, vcc
	s_nop 0
	v_fmac_f32_dpp v38, v34, v90 row_ror:1 row_mask:0xf bank_mask:0xf
	v_fmac_f32_dpp v39, v36, v74 row_ror:1 row_mask:0xf bank_mask:0xf
	v_cndmask_b32_e64 v35, v30, 0, s[2:3]
	v_cndmask_b32_e64 v37, v26, 0, s[2:3]
	s_nop 0
	v_fmac_f32_dpp v38, v35, v86 row_ror:2 row_mask:0xf bank_mask:0xf
	v_fmac_f32_dpp v39, v37, v82 row_ror:2 row_mask:0xf bank_mask:0xf
	v_fma_f32 v41, v31, v95, v71
	v_mul_f32_e32 v34, 0xbfb8aa3b, v38
	v_exp_f32_e32 v34, v34
	v_fma_f32 v42, v27, v79, v67
	v_cndmask_b32_e64 v35, v31, 0, vcc
	v_cndmask_b32_e64 v37, v27, 0, vcc
	v_add_f32_e32 v34, 1.0, v34
	v_rcp_f32_e32 v34, v34
	v_cndmask_b32_e64 v40, v27, 0, s[2:3]
	v_fmac_f32_dpp v41, v35, v91 row_ror:1 row_mask:0xf bank_mask:0xf
	v_fmac_f32_dpp v42, v37, v75 row_ror:1 row_mask:0xf bank_mask:0xf
	v_cndmask_b32_e64 v36, v31, 0, s[2:3]
	s_nop 1
	v_fmac_f32_dpp v41, v36, v87 row_ror:2 row_mask:0xf bank_mask:0xf
	v_fmac_f32_dpp v42, v40, v83 row_ror:2 row_mask:0xf bank_mask:0xf
	v_mul_f32_e32 v34, v38, v34
	v_fma_f32 v40, v32, v96, v72
	v_fma_f32 v43, v28, v80, v68
	v_mul_f32_e32 v34, v39, v34
	v_cndmask_b32_e64 v36, v32, 0, vcc
	v_cndmask_b32_e64 v37, v32, 0, s[2:3]
	v_cndmask_b32_e64 v38, v28, 0, vcc
	v_cndmask_b32_e64 v39, v28, 0, s[2:3]
	v_fmac_f32_dpp v40, v36, v92 row_ror:1 row_mask:0xf bank_mask:0xf
	v_fmac_f32_dpp v43, v38, v76 row_ror:1 row_mask:0xf bank_mask:0xf
	v_fma_f32 v46, v29, v81, v69
	v_fmac_f32_dpp v40, v37, v88 row_ror:2 row_mask:0xf bank_mask:0xf
	v_fmac_f32_dpp v43, v39, v84 row_ror:2 row_mask:0xf bank_mask:0xf
	v_cndmask_b32_e64 v37, v33, 0, vcc
	v_cndmask_b32_e64 v39, v29, 0, vcc
	s_nop 0
	v_fmac_f32_dpp v45, v37, v93 row_ror:1 row_mask:0xf bank_mask:0xf
	v_fmac_f32_dpp v46, v39, v77 row_ror:1 row_mask:0xf bank_mask:0xf
	v_mul_f32_e32 v35, 0xbfb8aa3b, v41
	v_mul_f32_e32 v36, 0xbfb8aa3b, v40
	v_cndmask_b32_e64 v38, v33, 0, s[2:3]
	v_cndmask_b32_e64 v44, v29, 0, s[2:3]
	s_nop 0
	v_fmac_f32_dpp v45, v38, v89 row_ror:2 row_mask:0xf bank_mask:0xf
	v_fmac_f32_dpp v46, v44, v85 row_ror:2 row_mask:0xf bank_mask:0xf
	v_exp_f32_e32 v35, v35
	v_mul_f32_e32 v37, 0xbfb8aa3b, v45
	v_exp_f32_e32 v36, v36
	v_exp_f32_e32 v37, v37
	v_add_f32_e32 v35, 1.0, v35
	v_rcp_f32_e32 v35, v35
	v_add_f32_e32 v36, 1.0, v36
	v_add_f32_e32 v37, 1.0, v37
	v_rcp_f32_e32 v36, v36
	v_rcp_f32_e32 v37, v37
	v_mul_f32_e32 v35, v41, v35
	v_mul_f32_e32 v35, v42, v35
	v_mul_f32_e32 v36, v40, v36
	v_mul_f32_e32 v37, v45, v37
	v_mul_f32_e32 v36, v43, v36
	v_mul_f32_e32 v37, v46, v37
	v_cvt_pk_bf16_f32 v34, v34, v35
	v_cvt_pk_bf16_f32 v35, v36, v37
	v_fma_f32 v36, v22, v94, v70
	v_fma_f32 v37, v18, v78, v66
	global_store_dwordx2 v[100:101], v[34:35], off offset:8
	v_cndmask_b32_e32 v34, v22, v30, vcc
	v_cndmask_b32_e32 v35, v18, v26, vcc
	v_cndmask_b32_e64 v26, v18, v26, s[2:3]
	v_fmac_f32_dpp v36, v34, v90 row_ror:1 row_mask:0xf bank_mask:0xf
	v_fmac_f32_dpp v37, v35, v74 row_ror:1 row_mask:0xf bank_mask:0xf
	v_cndmask_b32_e64 v30, v22, v30, s[2:3]
	s_nop 1
	v_fmac_f32_dpp v36, v30, v86 row_ror:2 row_mask:0xf bank_mask:0xf
	v_fmac_f32_dpp v37, v26, v82 row_ror:2 row_mask:0xf bank_mask:0xf
	v_cndmask_b32_e32 v34, v19, v27, vcc
	v_mul_f32_e32 v26, 0xbfb8aa3b, v36
	v_exp_f32_e32 v26, v26
	v_fma_f32 v35, v23, v95, v71
	v_fma_f32 v38, v19, v79, v67
	v_cndmask_b32_e32 v30, v23, v31, vcc
	v_add_f32_e32 v26, 1.0, v26
	v_rcp_f32_e32 v26, v26
	v_cndmask_b32_e64 v31, v23, v31, s[2:3]
	v_fmac_f32_dpp v35, v30, v91 row_ror:1 row_mask:0xf bank_mask:0xf
	v_fmac_f32_dpp v38, v34, v75 row_ror:1 row_mask:0xf bank_mask:0xf
	v_fma_f32 v34, v24, v96, v72
	v_mul_f32_e32 v26, v36, v26
	v_fma_f32 v36, v20, v80, v68
	v_cndmask_b32_e64 v27, v19, v27, s[2:3]
	s_nop 0
	v_fmac_f32_dpp v35, v31, v87 row_ror:2 row_mask:0xf bank_mask:0xf
	v_fmac_f32_dpp v38, v27, v83 row_ror:2 row_mask:0xf bank_mask:0xf
	v_cndmask_b32_e32 v30, v24, v32, vcc
	v_cndmask_b32_e64 v31, v24, v32, s[2:3]
	v_cndmask_b32_e32 v32, v20, v28, vcc
	s_nop 0
	v_fmac_f32_dpp v34, v30, v92 row_ror:1 row_mask:0xf bank_mask:0xf
	v_fmac_f32_dpp v36, v32, v76 row_ror:1 row_mask:0xf bank_mask:0xf
	v_mul_f32_e32 v26, v37, v26
	v_cndmask_b32_e64 v28, v20, v28, s[2:3]
	s_nop 0
	v_fmac_f32_dpp v34, v31, v88 row_ror:2 row_mask:0xf bank_mask:0xf
	v_fmac_f32_dpp v36, v28, v84 row_ror:2 row_mask:0xf bank_mask:0xf
	v_cndmask_b32_e32 v30, v25, v33, vcc
	v_cndmask_b32_e64 v31, v25, v33, s[2:3]
	v_fma_f32 v33, v25, v97, v73
	v_fma_f32 v37, v21, v81, v69
	v_cndmask_b32_e32 v32, v21, v29, vcc
	v_cndmask_b32_e64 v29, v21, v29, s[2:3]
	v_fmac_f32_dpp v33, v30, v93 row_ror:1 row_mask:0xf bank_mask:0xf
	v_fmac_f32_dpp v37, v32, v77 row_ror:1 row_mask:0xf bank_mask:0xf
	v_mul_f32_e32 v27, 0xbfb8aa3b, v35
	v_mul_f32_e32 v28, 0xbfb8aa3b, v34
	v_fmac_f32_dpp v33, v31, v89 row_ror:2 row_mask:0xf bank_mask:0xf
	v_fmac_f32_dpp v37, v29, v85 row_ror:2 row_mask:0xf bank_mask:0xf
	v_exp_f32_e32 v27, v27
	v_mul_f32_e32 v29, 0xbfb8aa3b, v33
	v_exp_f32_e32 v28, v28
	v_exp_f32_e32 v29, v29
	v_add_f32_e32 v27, 1.0, v27
	v_rcp_f32_e32 v27, v27
	v_add_f32_e32 v28, 1.0, v28
	v_add_f32_e32 v29, 1.0, v29
	v_rcp_f32_e32 v28, v28
	v_rcp_f32_e32 v29, v29
	v_mul_f32_e32 v27, v35, v27
	v_mul_f32_e32 v27, v38, v27
	v_mul_f32_e32 v28, v34, v28
	v_mul_f32_e32 v29, v33, v29
	v_mul_f32_e32 v28, v36, v28
	v_mul_f32_e32 v29, v37, v29
	v_cvt_pk_bf16_f32 v26, v26, v27
	v_cvt_pk_bf16_f32 v27, v28, v29
	v_fma_f32 v28, v14, v94, v70
	v_fma_f32 v29, v10, v78, v66
	global_store_dwordx2 v[102:103], v[26:27], off offset:8
	v_cndmask_b32_e32 v26, v14, v22, vcc
	v_cndmask_b32_e32 v27, v10, v18, vcc
	v_cndmask_b32_e64 v18, v10, v18, s[2:3]
	v_fmac_f32_dpp v28, v26, v90 row_ror:1 row_mask:0xf bank_mask:0xf
	v_fmac_f32_dpp v29, v27, v74 row_ror:1 row_mask:0xf bank_mask:0xf
	v_cndmask_b32_e64 v22, v14, v22, s[2:3]
	s_nop 1
	v_fmac_f32_dpp v28, v22, v86 row_ror:2 row_mask:0xf bank_mask:0xf
	v_fmac_f32_dpp v29, v18, v82 row_ror:2 row_mask:0xf bank_mask:0xf
	v_cndmask_b32_e32 v26, v11, v19, vcc
	v_mul_f32_e32 v18, 0xbfb8aa3b, v28
	v_exp_f32_e32 v18, v18
	v_fma_f32 v27, v15, v95, v71
	v_fma_f32 v30, v11, v79, v67
	v_cndmask_b32_e32 v22, v15, v23, vcc
	v_add_f32_e32 v18, 1.0, v18
	v_rcp_f32_e32 v18, v18
	v_cndmask_b32_e64 v23, v15, v23, s[2:3]
	v_fmac_f32_dpp v27, v22, v91 row_ror:1 row_mask:0xf bank_mask:0xf
	v_fmac_f32_dpp v30, v26, v75 row_ror:1 row_mask:0xf bank_mask:0xf
	v_fma_f32 v26, v16, v96, v72
	v_mul_f32_e32 v18, v28, v18
	v_fma_f32 v28, v12, v80, v68
	v_cndmask_b32_e64 v19, v11, v19, s[2:3]
	s_nop 0
	v_fmac_f32_dpp v27, v23, v87 row_ror:2 row_mask:0xf bank_mask:0xf
	v_fmac_f32_dpp v30, v19, v83 row_ror:2 row_mask:0xf bank_mask:0xf
	v_cndmask_b32_e32 v22, v16, v24, vcc
	v_cndmask_b32_e64 v23, v16, v24, s[2:3]
	v_cndmask_b32_e32 v24, v12, v20, vcc
	s_nop 0
	v_fmac_f32_dpp v26, v22, v92 row_ror:1 row_mask:0xf bank_mask:0xf
	v_fmac_f32_dpp v28, v24, v76 row_ror:1 row_mask:0xf bank_mask:0xf
	v_mul_f32_e32 v18, v29, v18
	v_cndmask_b32_e64 v20, v12, v20, s[2:3]
	s_nop 0
	v_fmac_f32_dpp v26, v23, v88 row_ror:2 row_mask:0xf bank_mask:0xf
	v_fmac_f32_dpp v28, v20, v84 row_ror:2 row_mask:0xf bank_mask:0xf
	v_cndmask_b32_e32 v22, v17, v25, vcc
	v_cndmask_b32_e64 v23, v17, v25, s[2:3]
	v_fma_f32 v25, v17, v97, v73
	v_fma_f32 v29, v13, v81, v69
	v_mul_f32_e32 v19, 0xbfb8aa3b, v27
	v_cndmask_b32_e32 v24, v13, v21, vcc
	v_cndmask_b32_e64 v21, v13, v21, s[2:3]
	v_fmac_f32_dpp v25, v22, v93 row_ror:1 row_mask:0xf bank_mask:0xf
	v_fmac_f32_dpp v29, v24, v77 row_ror:1 row_mask:0xf bank_mask:0xf
	v_exp_f32_e32 v19, v19
	v_mul_f32_e32 v20, 0xbfb8aa3b, v26
	v_fmac_f32_dpp v25, v23, v89 row_ror:2 row_mask:0xf bank_mask:0xf
	v_fmac_f32_dpp v29, v21, v85 row_ror:2 row_mask:0xf bank_mask:0xf
	v_exp_f32_e32 v20, v20
	v_mul_f32_e32 v21, 0xbfb8aa3b, v25
	v_exp_f32_e32 v21, v21
	v_add_f32_e32 v19, 1.0, v19
	v_rcp_f32_e32 v19, v19
	v_add_f32_e32 v20, 1.0, v20
	v_add_f32_e32 v21, 1.0, v21
	v_rcp_f32_e32 v20, v20
	v_rcp_f32_e32 v21, v21
	v_mul_f32_e32 v19, v27, v19
	v_mul_f32_e32 v19, v30, v19
	v_mul_f32_e32 v20, v26, v20
	v_mul_f32_e32 v21, v25, v21
	v_mul_f32_e32 v20, v28, v20
	v_mul_f32_e32 v21, v29, v21
	v_cvt_pk_bf16_f32 v18, v18, v19
	v_cvt_pk_bf16_f32 v19, v20, v21
	global_store_dwordx2 v[104:105], v[18:19], off offset:8
	v_cndmask_b32_e32 v18, v6, v14, vcc
	v_cndmask_b32_e64 v14, v6, v14, s[2:3]
	v_cndmask_b32_e32 v19, v2, v10, vcc
	v_cndmask_b32_e64 v10, v2, v10, s[2:3]
	v_fma_f32 v6, v6, v94, v70
	v_fma_f32 v2, v2, v78, v66
	s_nop 0
	v_fmac_f32_dpp v6, v18, v90 row_ror:1 row_mask:0xf bank_mask:0xf
	v_fmac_f32_dpp v2, v19, v74 row_ror:1 row_mask:0xf bank_mask:0xf
	v_cndmask_b32_e32 v18, v3, v11, vcc
	v_fmac_f32_dpp v6, v14, v86 row_ror:2 row_mask:0xf bank_mask:0xf
	v_fmac_f32_dpp v2, v10, v82 row_ror:2 row_mask:0xf bank_mask:0xf
	v_cndmask_b32_e32 v14, v7, v15, vcc
	v_mul_f32_e32 v10, 0xbfb8aa3b, v6
	v_exp_f32_e32 v10, v10
	v_cndmask_b32_e64 v15, v7, v15, s[2:3]
	v_cndmask_b32_e64 v11, v3, v11, s[2:3]
	v_fma_f32 v7, v7, v95, v71
	v_fma_f32 v3, v3, v79, v67
	v_add_f32_e32 v10, 1.0, v10
	v_fmac_f32_dpp v7, v14, v91 row_ror:1 row_mask:0xf bank_mask:0xf
	v_fmac_f32_dpp v3, v18, v75 row_ror:1 row_mask:0xf bank_mask:0xf
	v_rcp_f32_e32 v10, v10
	v_fmac_f32_dpp v7, v15, v87 row_ror:2 row_mask:0xf bank_mask:0xf
	v_fmac_f32_dpp v3, v11, v83 row_ror:2 row_mask:0xf bank_mask:0xf
	v_cndmask_b32_e32 v14, v4, v12, vcc
	v_mul_f32_e32 v11, 0xbfb8aa3b, v7
	v_exp_f32_e32 v11, v11
	v_mul_f32_e32 v6, v6, v10
	v_mul_f32_e32 v2, v2, v6
	v_cndmask_b32_e32 v10, v8, v16, vcc
	v_add_f32_e32 v6, 1.0, v11
	v_cndmask_b32_e64 v11, v8, v16, s[2:3]
	v_cndmask_b32_e64 v12, v4, v12, s[2:3]
	v_fma_f32 v8, v8, v96, v72
	v_fma_f32 v4, v4, v80, v68
	s_nop 0
	v_fmac_f32_dpp v8, v10, v92 row_ror:1 row_mask:0xf bank_mask:0xf
	v_fmac_f32_dpp v4, v14, v76 row_ror:1 row_mask:0xf bank_mask:0xf
	v_fmac_f32_e32 v73, v9, v97
	v_fmac_f32_e32 v69, v5, v81
	v_fmac_f32_dpp v8, v11, v88 row_ror:2 row_mask:0xf bank_mask:0xf
	v_fmac_f32_dpp v4, v12, v84 row_ror:2 row_mask:0xf bank_mask:0xf
	v_cndmask_b32_e32 v11, v9, v17, vcc
	v_cndmask_b32_e32 v14, v5, v13, vcc
	s_nop 0
	v_fmac_f32_dpp v73, v11, v93 row_ror:1 row_mask:0xf bank_mask:0xf
	v_fmac_f32_dpp v69, v14, v77 row_ror:1 row_mask:0xf bank_mask:0xf
	v_mul_f32_e32 v10, 0xbfb8aa3b, v8
	v_cndmask_b32_e64 v12, v9, v17, s[2:3]
	v_cndmask_b32_e64 v13, v5, v13, s[2:3]
	s_nop 0
	v_fmac_f32_dpp v73, v12, v89 row_ror:2 row_mask:0xf bank_mask:0xf
	v_fmac_f32_dpp v69, v13, v85 row_ror:2 row_mask:0xf bank_mask:0xf
	v_rcp_f32_e32 v6, v6
	v_mul_f32_e32 v5, 0xbfb8aa3b, v73
	v_exp_f32_e32 v10, v10
	v_exp_f32_e32 v5, v5
	v_mul_f32_e32 v6, v7, v6
	v_mul_f32_e32 v3, v3, v6
	v_add_f32_e32 v7, 1.0, v10
	v_add_f32_e32 v5, 1.0, v5
	v_rcp_f32_e32 v7, v7
	v_rcp_f32_e32 v5, v5
	v_cvt_pk_bf16_f32 v2, v2, v3
	s_and_b64 vcc, exec, s[0:1]
	v_mul_f32_e32 v6, v8, v7
	v_mul_f32_e32 v5, v73, v5
	v_mul_f32_e32 v4, v4, v6
	v_mul_f32_e32 v5, v69, v5
	v_cvt_pk_bf16_f32 v3, v4, v5
	global_store_dwordx2 v[106:107], v[2:3], off offset:8
	s_mov_b64 s[0:1], -1
	s_cbranch_vccnz .LBB0_730
	s_andn2_b64 vcc, exec, s[10:11]
	s_cbranch_vccnz .LBB0_729
	s_barrier
	s_branch .LBB0_729
